# v7: v6 + MLP-in (EpiMlp1) epilogues of the two wave groups overlapped (group 1 copy before its last loop barrier)
# baseline (speedup 1.0000x reference)
.LBB0_999:
	ds_read_b128 v[156:159], v152
	ds_read_b128 v[160:163], v152 offset:1024
	ds_read_b128 v[164:167], v152 offset:2048
	ds_read_b128 v[168:171], v152 offset:3072
	s_add_u32 s20, s46, 0xfff80080
	s_addc_u32 s21, s47, -1
	s_cmp_eq_u32 s58, 28
	s_cselect_b32 s21, s15, s21
	s_cselect_b32 s20, s54, s20
	s_cselect_b32 s49, s11, s57
	s_cselect_b32 s48, s55, s56
	v_lshl_add_u64 v[148:149], s[46:47], 0, v[136:137]
	s_add_i32 m0, s35, 0xc000
	ds_read_b128 v[172:175], v153
	ds_read_b128 v[176:179], v153 offset:1024
	ds_read_b128 v[180:183], v153 offset:2048
	ds_read_b128 v[184:187], v153 offset:3072
	ds_read_b128 v[188:191], v153 offset:4096
	ds_read_b128 v[196:199], v153 offset:5120
	ds_read_b128 v[200:203], v153 offset:6144
	ds_read_b128 v[204:207], v153 offset:7168
	global_load_lds_dwordx4 v[148:149], off
	v_lshl_add_u64 v[148:149], s[46:47], 0, v[138:139]
	s_add_i32 m0, s35, 0xe000
	s_nop 0
	global_load_lds_dwordx4 v[148:149], off
	s_waitcnt lgkmcnt(8)
	s_barrier
	s_waitcnt lgkmcnt(0)
	s_setprio 1
	s_waitcnt lgkmcnt(0)
	v_mfma_f32_16x16x32_bf16 v[124:127], v[156:159], v[172:175], v[124:127]
	v_mfma_f32_16x16x32_bf16 v[120:123], v[164:167], v[172:175], v[120:123]
	v_mfma_f32_16x16x32_bf16 v[108:111], v[156:159], v[180:183], v[108:111]
	v_mfma_f32_16x16x32_bf16 v[104:107], v[164:167], v[180:183], v[104:107]
	v_mfma_f32_16x16x32_bf16 v[92:95], v[156:159], v[188:191], v[92:95]
	v_mfma_f32_16x16x32_bf16 v[88:91], v[164:167], v[188:191], v[88:91]
	v_mfma_f32_16x16x32_bf16 v[76:79], v[156:159], v[200:203], v[76:79]
	v_mfma_f32_16x16x32_bf16 v[72:75], v[164:167], v[200:203], v[72:75]
	v_mfma_f32_16x16x32_bf16 v[124:127], v[160:163], v[176:179], v[124:127]
	v_mfma_f32_16x16x32_bf16 v[120:123], v[168:171], v[176:179], v[120:123]
	v_mfma_f32_16x16x32_bf16 v[108:111], v[160:163], v[184:187], v[108:111]
	v_mfma_f32_16x16x32_bf16 v[104:107], v[168:171], v[184:187], v[104:107]
	v_mfma_f32_16x16x32_bf16 v[92:95], v[160:163], v[196:199], v[92:95]
	v_mfma_f32_16x16x32_bf16 v[88:91], v[168:171], v[196:199], v[88:91]
	v_mfma_f32_16x16x32_bf16 v[76:79], v[160:163], v[204:207], v[76:79]
	v_mfma_f32_16x16x32_bf16 v[72:75], v[168:171], v[204:207], v[72:75]
	s_setprio 0
	s_barrier
	s_add_i32 s59, s52, s23
	v_lshl_add_u64 v[148:149], s[48:49], 0, v[132:133]
	s_mov_b32 m0, s59
	ds_read_b128 v[208:211], v154
	ds_read_b128 v[212:215], v154 offset:1024
	ds_read_b128 v[216:219], v154 offset:2048
	ds_read_b128 v[220:223], v154 offset:3072
	global_load_lds_dwordx4 v[148:149], off
	v_lshl_add_u64 v[224:225], s[48:49], 0, v[128:129]
	s_add_i32 m0, s59, 0x2000
	s_nop 0
	global_load_lds_dwordx4 v[224:225], off
	s_barrier
	s_waitcnt lgkmcnt(0)
	s_setprio 1
	s_waitcnt lgkmcnt(0)
	v_mfma_f32_16x16x32_bf16 v[116:119], v[208:211], v[172:175], v[116:119]
	v_mfma_f32_16x16x32_bf16 v[112:115], v[216:219], v[172:175], v[112:115]
	v_mfma_f32_16x16x32_bf16 v[100:103], v[208:211], v[180:183], v[100:103]
	v_mfma_f32_16x16x32_bf16 v[96:99], v[216:219], v[180:183], v[96:99]
	v_mfma_f32_16x16x32_bf16 v[84:87], v[208:211], v[188:191], v[84:87]
	v_mfma_f32_16x16x32_bf16 v[80:83], v[216:219], v[188:191], v[80:83]
	v_mfma_f32_16x16x32_bf16 v[68:71], v[208:211], v[200:203], v[68:71]
	v_mfma_f32_16x16x32_bf16 v[64:67], v[216:219], v[200:203], v[64:67]
	v_mfma_f32_16x16x32_bf16 v[116:119], v[212:215], v[176:179], v[116:119]
	v_mfma_f32_16x16x32_bf16 v[112:115], v[220:223], v[176:179], v[112:115]
	v_mfma_f32_16x16x32_bf16 v[100:103], v[212:215], v[184:187], v[100:103]
	v_mfma_f32_16x16x32_bf16 v[96:99], v[220:223], v[184:187], v[96:99]
	v_mfma_f32_16x16x32_bf16 v[84:87], v[212:215], v[196:199], v[84:87]
	v_mfma_f32_16x16x32_bf16 v[80:83], v[220:223], v[196:199], v[80:83]
	v_mfma_f32_16x16x32_bf16 v[68:71], v[212:215], v[204:207], v[68:71]
	v_mfma_f32_16x16x32_bf16 v[64:67], v[220:223], v[204:207], v[64:67]
	s_setprio 0
	s_mov_b32 m0, s35
	v_lshl_add_u64 v[226:227], s[20:21], 0, v[134:135]
	s_barrier
	ds_read_b128 v[172:175], v153 offset:16384
	ds_read_b128 v[176:179], v153 offset:17408
	ds_read_b128 v[180:183], v153 offset:18432
	ds_read_b128 v[184:187], v153 offset:19456
	ds_read_b128 v[188:191], v153 offset:20480
	ds_read_b128 v[196:199], v153 offset:21504
	ds_read_b128 v[200:203], v153 offset:22528
	ds_read_b128 v[204:207], v153 offset:23552
	global_load_lds_dwordx4 v[226:227], off
	v_lshl_add_u64 v[228:229], s[20:21], 0, v[130:131]
	s_mov_b32 m0, s36
	s_nop 0
	global_load_lds_dwordx4 v[228:229], off
	s_barrier
	s_waitcnt lgkmcnt(0)
	s_setprio 1
	s_waitcnt lgkmcnt(0)
	v_mfma_f32_16x16x32_bf16 v[60:63], v[156:159], v[172:175], v[60:63]
	v_mfma_f32_16x16x32_bf16 v[56:59], v[164:167], v[172:175], v[56:59]
	v_mfma_f32_16x16x32_bf16 v[44:47], v[156:159], v[180:183], v[44:47]
	v_mfma_f32_16x16x32_bf16 v[40:43], v[164:167], v[180:183], v[40:43]
	v_mfma_f32_16x16x32_bf16 v[28:31], v[156:159], v[188:191], v[28:31]
	v_mfma_f32_16x16x32_bf16 v[24:27], v[164:167], v[188:191], v[24:27]
	v_mfma_f32_16x16x32_bf16 v[12:15], v[156:159], v[200:203], v[12:15]
	v_mfma_f32_16x16x32_bf16 v[8:11], v[164:167], v[200:203], v[8:11]
	v_mfma_f32_16x16x32_bf16 v[60:63], v[160:163], v[176:179], v[60:63]
	v_mfma_f32_16x16x32_bf16 v[56:59], v[168:171], v[176:179], v[56:59]
	v_mfma_f32_16x16x32_bf16 v[44:47], v[160:163], v[184:187], v[44:47]
	v_mfma_f32_16x16x32_bf16 v[40:43], v[168:171], v[184:187], v[40:43]
	v_mfma_f32_16x16x32_bf16 v[28:31], v[160:163], v[196:199], v[28:31]
	v_mfma_f32_16x16x32_bf16 v[24:27], v[168:171], v[196:199], v[24:27]
	v_mfma_f32_16x16x32_bf16 v[12:15], v[160:163], v[204:207], v[12:15]
	v_mfma_f32_16x16x32_bf16 v[8:11], v[168:171], v[204:207], v[8:11]
	s_setprio 0
	s_barrier
	s_add_u32 s60, s48, 0x80000
	s_addc_u32 s61, s49, 0
	s_add_i32 s59, s53, s23
	v_lshl_add_u64 v[156:157], s[60:61], 0, v[132:133]
	s_mov_b32 m0, s59
	s_nop 0
	global_load_lds_dwordx4 v[156:157], off
	v_lshl_add_u64 v[156:157], s[60:61], 0, v[128:129]
	s_add_i32 m0, s59, 0x2000
	s_nop 0
	global_load_lds_dwordx4 v[156:157], off
	s_waitcnt vmcnt(6)
	s_barrier
	s_setprio 1
	v_mfma_f32_16x16x32_bf16 v[52:55], v[208:211], v[172:175], v[52:55]
	v_mfma_f32_16x16x32_bf16 v[48:51], v[216:219], v[172:175], v[48:51]
	v_mfma_f32_16x16x32_bf16 v[36:39], v[208:211], v[180:183], v[36:39]
	v_mfma_f32_16x16x32_bf16 v[32:35], v[216:219], v[180:183], v[32:35]
	v_mfma_f32_16x16x32_bf16 v[20:23], v[208:211], v[188:191], v[20:23]
	v_mfma_f32_16x16x32_bf16 v[16:19], v[216:219], v[188:191], v[16:19]
	v_mfma_f32_16x16x32_bf16 v[4:7], v[208:211], v[200:203], v[4:7]
	v_mfma_f32_16x16x32_bf16 v[0:3], v[216:219], v[200:203], v[0:3]
	v_mfma_f32_16x16x32_bf16 v[52:55], v[212:215], v[176:179], v[52:55]
	v_mfma_f32_16x16x32_bf16 v[48:51], v[220:223], v[176:179], v[48:51]
	v_mfma_f32_16x16x32_bf16 v[36:39], v[212:215], v[184:187], v[36:39]
	v_mfma_f32_16x16x32_bf16 v[32:35], v[220:223], v[184:187], v[32:35]
	v_mfma_f32_16x16x32_bf16 v[20:23], v[212:215], v[196:199], v[20:23]
	v_mfma_f32_16x16x32_bf16 v[16:19], v[220:223], v[196:199], v[16:19]
	v_mfma_f32_16x16x32_bf16 v[4:7], v[212:215], v[204:207], v[4:7]
	v_mfma_f32_16x16x32_bf16 v[0:3], v[220:223], v[204:207], v[0:3]
	s_setprio 0
	s_add_i32 s59, 0, 0x18000
	v_add_u32_e32 v155, s59, v150
	s_barrier
	ds_read_b128 v[156:159], v155
	ds_read_b128 v[160:163], v155 offset:1024
	ds_read_b128 v[164:167], v155 offset:2048
	ds_read_b128 v[168:171], v155 offset:3072
	s_add_u32 s20, s20, 0x80000
	s_addc_u32 s21, s21, 0
	s_mov_b32 m0, s37
	v_lshl_add_u64 v[208:209], s[20:21], 0, v[134:135]
	ds_read_b128 v[172:175], v153 offset:32768
	ds_read_b128 v[176:179], v153 offset:33792
	ds_read_b128 v[180:183], v153 offset:34816
	ds_read_b128 v[184:187], v153 offset:35840
	ds_read_b128 v[188:191], v153 offset:36864
	ds_read_b128 v[196:199], v153 offset:37888
	ds_read_b128 v[200:203], v153 offset:38912
	ds_read_b128 v[204:207], v153 offset:39936
	global_load_lds_dwordx4 v[208:209], off
	v_lshl_add_u64 v[208:209], s[20:21], 0, v[130:131]
	s_mov_b32 m0, s38
	s_nop 0
	global_load_lds_dwordx4 v[208:209], off
	s_waitcnt lgkmcnt(8)
	s_barrier
	s_waitcnt lgkmcnt(0)
	s_setprio 1
	s_waitcnt lgkmcnt(0)
	v_mfma_f32_16x16x32_bf16 v[124:127], v[156:159], v[172:175], v[124:127]
	v_mfma_f32_16x16x32_bf16 v[120:123], v[164:167], v[172:175], v[120:123]
	v_mfma_f32_16x16x32_bf16 v[108:111], v[156:159], v[180:183], v[108:111]
	v_mfma_f32_16x16x32_bf16 v[104:107], v[164:167], v[180:183], v[104:107]
	v_mfma_f32_16x16x32_bf16 v[92:95], v[156:159], v[188:191], v[92:95]
	v_mfma_f32_16x16x32_bf16 v[88:91], v[164:167], v[188:191], v[88:91]
	v_mfma_f32_16x16x32_bf16 v[76:79], v[156:159], v[200:203], v[76:79]
	v_mfma_f32_16x16x32_bf16 v[72:75], v[164:167], v[200:203], v[72:75]
	v_mfma_f32_16x16x32_bf16 v[124:127], v[160:163], v[176:179], v[124:127]
	v_mfma_f32_16x16x32_bf16 v[120:123], v[168:171], v[176:179], v[120:123]
	v_mfma_f32_16x16x32_bf16 v[108:111], v[160:163], v[184:187], v[108:111]
	v_mfma_f32_16x16x32_bf16 v[104:107], v[168:171], v[184:187], v[104:107]
	v_mfma_f32_16x16x32_bf16 v[92:95], v[160:163], v[196:199], v[92:95]
	v_mfma_f32_16x16x32_bf16 v[88:91], v[168:171], v[196:199], v[88:91]
	v_mfma_f32_16x16x32_bf16 v[76:79], v[160:163], v[204:207], v[76:79]
	v_mfma_f32_16x16x32_bf16 v[72:75], v[168:171], v[204:207], v[72:75]
	s_setprio 0
	s_barrier
	s_add_i32 s60, 0, 0x1c000
	s_add_i32 s20, s59, s23
	v_add_u32_e32 v155, s60, v150
	v_lshl_add_u64 v[148:149], v[148:149], 0, s[8:9]
	s_mov_b32 m0, s20
	ds_read_b128 v[208:211], v155
	ds_read_b128 v[212:215], v155 offset:1024
	ds_read_b128 v[216:219], v155 offset:2048
	ds_read_b128 v[220:223], v155 offset:3072
	global_load_lds_dwordx4 v[148:149], off
	v_lshl_add_u64 v[148:149], v[224:225], 0, s[8:9]
	s_add_i32 m0, s20, 0x2000
	s_nop 0
	global_load_lds_dwordx4 v[148:149], off
	s_barrier
	s_waitcnt lgkmcnt(0)
	s_setprio 1
	s_waitcnt lgkmcnt(0)
	v_mfma_f32_16x16x32_bf16 v[116:119], v[208:211], v[172:175], v[116:119]
	v_mfma_f32_16x16x32_bf16 v[112:115], v[216:219], v[172:175], v[112:115]
	v_mfma_f32_16x16x32_bf16 v[100:103], v[208:211], v[180:183], v[100:103]
	v_mfma_f32_16x16x32_bf16 v[96:99], v[216:219], v[180:183], v[96:99]
	v_mfma_f32_16x16x32_bf16 v[84:87], v[208:211], v[188:191], v[84:87]
	v_mfma_f32_16x16x32_bf16 v[80:83], v[216:219], v[188:191], v[80:83]
	v_mfma_f32_16x16x32_bf16 v[68:71], v[208:211], v[200:203], v[68:71]
	v_mfma_f32_16x16x32_bf16 v[64:67], v[216:219], v[200:203], v[64:67]
	v_mfma_f32_16x16x32_bf16 v[116:119], v[212:215], v[176:179], v[116:119]
	v_mfma_f32_16x16x32_bf16 v[112:115], v[220:223], v[176:179], v[112:115]
	v_mfma_f32_16x16x32_bf16 v[100:103], v[212:215], v[184:187], v[100:103]
	v_mfma_f32_16x16x32_bf16 v[96:99], v[220:223], v[184:187], v[96:99]
	v_mfma_f32_16x16x32_bf16 v[84:87], v[212:215], v[196:199], v[84:87]
	v_mfma_f32_16x16x32_bf16 v[80:83], v[220:223], v[196:199], v[80:83]
	v_mfma_f32_16x16x32_bf16 v[68:71], v[212:215], v[204:207], v[68:71]
	v_mfma_f32_16x16x32_bf16 v[64:67], v[220:223], v[204:207], v[64:67]
	s_setprio 0
	s_mov_b32 m0, s45
	v_lshl_add_u64 v[148:149], v[226:227], 0, s[8:9]
	s_barrier
	ds_read_b128 v[172:175], v153 offset:49152
	ds_read_b128 v[176:179], v153 offset:50176
	ds_read_b128 v[180:183], v153 offset:51200
	ds_read_b128 v[184:187], v153 offset:52224
	ds_read_b128 v[188:191], v153 offset:53248
	ds_read_b128 v[196:199], v153 offset:54272
	ds_read_b128 v[200:203], v153 offset:55296
	ds_read_b128 v[204:207], v153 offset:56320
	global_load_lds_dwordx4 v[148:149], off
	v_lshl_add_u64 v[148:149], v[228:229], 0, s[8:9]
	s_mov_b32 m0, s50
	s_nop 0
	global_load_lds_dwordx4 v[148:149], off
	s_barrier
	s_waitcnt lgkmcnt(0)
	s_setprio 1
	s_waitcnt lgkmcnt(0)
	v_mfma_f32_16x16x32_bf16 v[60:63], v[156:159], v[172:175], v[60:63]
	v_mfma_f32_16x16x32_bf16 v[56:59], v[164:167], v[172:175], v[56:59]
	v_mfma_f32_16x16x32_bf16 v[44:47], v[156:159], v[180:183], v[44:47]
	v_mfma_f32_16x16x32_bf16 v[40:43], v[164:167], v[180:183], v[40:43]
	v_mfma_f32_16x16x32_bf16 v[28:31], v[156:159], v[188:191], v[28:31]
	v_mfma_f32_16x16x32_bf16 v[24:27], v[164:167], v[188:191], v[24:27]
	v_mfma_f32_16x16x32_bf16 v[12:15], v[156:159], v[200:203], v[12:15]
	v_mfma_f32_16x16x32_bf16 v[8:11], v[164:167], v[200:203], v[8:11]
	v_mfma_f32_16x16x32_bf16 v[60:63], v[160:163], v[176:179], v[60:63]
	v_mfma_f32_16x16x32_bf16 v[56:59], v[168:171], v[176:179], v[56:59]
	v_mfma_f32_16x16x32_bf16 v[44:47], v[160:163], v[184:187], v[44:47]
	v_mfma_f32_16x16x32_bf16 v[40:43], v[168:171], v[184:187], v[40:43]
	v_mfma_f32_16x16x32_bf16 v[28:31], v[160:163], v[196:199], v[28:31]
	v_mfma_f32_16x16x32_bf16 v[24:27], v[168:171], v[196:199], v[24:27]
	v_mfma_f32_16x16x32_bf16 v[12:15], v[160:163], v[204:207], v[12:15]
	v_mfma_f32_16x16x32_bf16 v[8:11], v[168:171], v[204:207], v[8:11]
	s_setprio 0
	s_barrier
	s_add_u32 s20, s48, 0x80080
	s_addc_u32 s21, s49, 0
	s_add_i32 s48, s60, s23
	v_lshl_add_u64 v[148:149], s[20:21], 0, v[132:133]
	s_mov_b32 m0, s48
	s_nop 0
	global_load_lds_dwordx4 v[148:149], off
	v_lshl_add_u64 v[148:149], s[20:21], 0, v[128:129]
	s_add_i32 m0, s48, 0x2000
	s_nop 0
	global_load_lds_dwordx4 v[148:149], off
	s_waitcnt vmcnt(6)
	s_barrier
	s_setprio 1
	v_mfma_f32_16x16x32_bf16 v[52:55], v[208:211], v[172:175], v[52:55]
	v_mfma_f32_16x16x32_bf16 v[48:51], v[216:219], v[172:175], v[48:51]
	v_mfma_f32_16x16x32_bf16 v[36:39], v[208:211], v[180:183], v[36:39]
	v_mfma_f32_16x16x32_bf16 v[32:35], v[216:219], v[180:183], v[32:35]
	v_mfma_f32_16x16x32_bf16 v[20:23], v[208:211], v[188:191], v[20:23]
	v_mfma_f32_16x16x32_bf16 v[16:19], v[216:219], v[188:191], v[16:19]
	v_mfma_f32_16x16x32_bf16 v[4:7], v[208:211], v[200:203], v[4:7]
	v_mfma_f32_16x16x32_bf16 v[0:3], v[216:219], v[200:203], v[0:3]
	v_mfma_f32_16x16x32_bf16 v[52:55], v[212:215], v[176:179], v[52:55]
	v_mfma_f32_16x16x32_bf16 v[48:51], v[220:223], v[176:179], v[48:51]
	v_mfma_f32_16x16x32_bf16 v[36:39], v[212:215], v[184:187], v[36:39]
	v_mfma_f32_16x16x32_bf16 v[32:35], v[220:223], v[184:187], v[32:35]
	v_mfma_f32_16x16x32_bf16 v[20:23], v[212:215], v[196:199], v[20:23]
	v_mfma_f32_16x16x32_bf16 v[16:19], v[220:223], v[196:199], v[16:19]
	v_mfma_f32_16x16x32_bf16 v[4:7], v[212:215], v[204:207], v[4:7]
	v_mfma_f32_16x16x32_bf16 v[0:3], v[220:223], v[204:207], v[0:3]
	s_setprio 0
	s_add_i32 s58, s58, 2
	s_add_u32 s46, s46, 0x100
	s_addc_u32 s47, s47, 0
	s_add_u32 s56, s56, 0x100
	s_addc_u32 s57, s57, 0
	s_cmp_gt_u32 s58, 29
	s_cbranch_scc0 .Ldup_nl_mlpin0
	s_cmpk_gt_u32 s12, 0xff
	s_cbranch_scc0 .Ldup_nl_mlpin0
	v_lshl_add_u32 v148, s44, 8, v147
	v_max_f32_e32 v124, v124, v124
	v_max_f32_e32 v120, v120, v120
	v_ashrrev_i32_e32 v149, 31, v148
	v_max_f32_e32 v124, 0, v124
	v_max_f32_e32 v120, 0, v120
	v_lshlrev_b64 v[158:159], 14, v[148:149]
	v_mul_f32_e32 v149, v124, v124
	v_mul_f32_e32 v124, v120, v120
	v_max_f32_e32 v120, v125, v125
	v_max_f32_e32 v121, v121, v121
	v_max_f32_e32 v120, 0, v120
	v_max_f32_e32 v121, 0, v121
	v_mul_f32_e32 v155, v120, v120
	v_mul_f32_e32 v160, v121, v121
	v_max_f32_e32 v120, v126, v126
	v_max_f32_e32 v121, v122, v122
	v_max_f32_e32 v120, 0, v120
	v_max_f32_e32 v121, 0, v121
	v_lshl_or_b32 v156, s33, 8, v151
	v_mul_f32_e32 v161, v120, v120
	v_mul_f32_e32 v125, v121, v121
	v_max_f32_e32 v120, v127, v127
	v_max_f32_e32 v121, v123, v123
	v_max_f32_e32 v116, v116, v116
	v_max_f32_e32 v112, v112, v112
	v_max_f32_e32 v117, v117, v117
	v_max_f32_e32 v113, v113, v113
	v_max_f32_e32 v118, v118, v118
	v_max_f32_e32 v114, v114, v114
	v_max_f32_e32 v119, v119, v119
	v_max_f32_e32 v115, v115, v115
	v_ashrrev_i32_e32 v157, 31, v156
	v_max_f32_e32 v120, 0, v120
	v_max_f32_e32 v121, 0, v121
	v_max_f32_e32 v116, 0, v116
	v_max_f32_e32 v112, 0, v112
	v_max_f32_e32 v117, 0, v117
	v_max_f32_e32 v113, 0, v113
	v_max_f32_e32 v118, 0, v118
	v_max_f32_e32 v114, 0, v114
	v_max_f32_e32 v119, 0, v119
	v_max_f32_e32 v115, 0, v115
	v_mul_f32_e32 v162, v120, v120
	v_mul_f32_e32 v163, v121, v121
	v_lshl_add_u64 v[122:123], s[28:29], 0, v[158:159]
	v_lshlrev_b64 v[120:121], 1, v[156:157]
	v_mul_f32_e32 v116, v116, v116
	v_mul_f32_e32 v112, v112, v112
	v_mul_f32_e32 v117, v117, v117
	v_mul_f32_e32 v113, v113, v113
	v_mul_f32_e32 v118, v118, v118
	v_mul_f32_e32 v114, v114, v114
	v_mul_f32_e32 v119, v119, v119
	v_mul_f32_e32 v115, v115, v115
	v_max_f32_e32 v104, v104, v104
	v_lshl_add_u64 v[126:127], v[122:123], 0, v[120:121]
	v_cvt_pk_bf16_f32 v115, v114, v115
	v_cvt_pk_bf16_f32 v114, v112, v113
	v_cvt_pk_bf16_f32 v113, v118, v119
	v_cvt_pk_bf16_f32 v112, v116, v117
	v_max_f32_e32 v104, 0, v104
	global_store_dwordx4 v[126:127], v[112:115], off offset:256
	v_max_f32_e32 v105, v105, v105
	v_max_f32_e32 v105, 0, v105
	v_mul_f32_e32 v115, v104, v104
	v_max_f32_e32 v104, v109, v109
	v_max_f32_e32 v104, 0, v104
	v_mul_f32_e32 v116, v104, v104
	v_mul_f32_e32 v117, v105, v105
	v_max_f32_e32 v104, v110, v110
	v_max_f32_e32 v105, v106, v106
	v_or_b32_e32 v112, 16, v148
	v_max_f32_e32 v104, 0, v104
	v_max_f32_e32 v105, 0, v105
	v_ashrrev_i32_e32 v113, 31, v112
	v_mul_f32_e32 v110, v104, v104
	v_mul_f32_e32 v106, v105, v105
	v_max_f32_e32 v104, v111, v111
	v_max_f32_e32 v105, v107, v107
	v_max_f32_e32 v100, v100, v100
	v_max_f32_e32 v96, v96, v96
	v_max_f32_e32 v101, v101, v101
	v_max_f32_e32 v97, v97, v97
	v_max_f32_e32 v102, v102, v102
	v_max_f32_e32 v98, v98, v98
	v_max_f32_e32 v103, v103, v103
	v_max_f32_e32 v99, v99, v99
	v_lshlrev_b64 v[112:113], 14, v[112:113]
	v_max_f32_e32 v108, v108, v108
	v_max_f32_e32 v104, 0, v104
	v_max_f32_e32 v105, 0, v105
	v_max_f32_e32 v100, 0, v100
	v_max_f32_e32 v96, 0, v96
	v_max_f32_e32 v101, 0, v101
	v_max_f32_e32 v97, 0, v97
	v_max_f32_e32 v102, 0, v102
	v_max_f32_e32 v98, 0, v98
	v_max_f32_e32 v103, 0, v103
	v_max_f32_e32 v99, 0, v99
	v_max_f32_e32 v108, 0, v108
	v_mul_f32_e32 v111, v104, v104
	v_mul_f32_e32 v107, v105, v105
	v_lshl_add_u64 v[104:105], s[28:29], 0, v[112:113]
	v_mul_f32_e32 v100, v100, v100
	v_mul_f32_e32 v96, v96, v96
	v_mul_f32_e32 v101, v101, v101
	v_mul_f32_e32 v97, v97, v97
	v_mul_f32_e32 v102, v102, v102
	v_mul_f32_e32 v98, v98, v98
	v_mul_f32_e32 v103, v103, v103
	v_mul_f32_e32 v99, v99, v99
	v_max_f32_e32 v88, v88, v88
	v_mul_f32_e32 v114, v108, v108
	v_lshl_add_u64 v[108:109], v[104:105], 0, v[120:121]
	v_cvt_pk_bf16_f32 v99, v98, v99
	v_cvt_pk_bf16_f32 v98, v96, v97
	v_cvt_pk_bf16_f32 v97, v102, v103
	v_cvt_pk_bf16_f32 v96, v100, v101
	v_max_f32_e32 v88, 0, v88
	global_store_dwordx4 v[108:109], v[96:99], off offset:256
	v_max_f32_e32 v89, v89, v89
	v_max_f32_e32 v89, 0, v89
	v_mul_f32_e32 v99, v88, v88
	v_max_f32_e32 v88, v93, v93
	v_max_f32_e32 v88, 0, v88
	v_mul_f32_e32 v100, v88, v88
	v_mul_f32_e32 v101, v89, v89
	v_max_f32_e32 v88, v94, v94
	v_max_f32_e32 v89, v90, v90
	v_or_b32_e32 v96, 32, v148
	v_max_f32_e32 v88, 0, v88
	v_max_f32_e32 v89, 0, v89
	v_ashrrev_i32_e32 v97, 31, v96
	v_mul_f32_e32 v94, v88, v88
	v_mul_f32_e32 v90, v89, v89
	v_max_f32_e32 v88, v95, v95
	v_max_f32_e32 v89, v91, v91
	v_max_f32_e32 v84, v84, v84
	v_max_f32_e32 v80, v80, v80
	v_max_f32_e32 v85, v85, v85
	v_max_f32_e32 v81, v81, v81
	v_max_f32_e32 v86, v86, v86
	v_max_f32_e32 v82, v82, v82
	v_max_f32_e32 v87, v87, v87
	v_max_f32_e32 v83, v83, v83
	v_lshlrev_b64 v[96:97], 14, v[96:97]
	v_max_f32_e32 v92, v92, v92
	v_max_f32_e32 v88, 0, v88
	v_max_f32_e32 v89, 0, v89
	v_max_f32_e32 v84, 0, v84
	v_max_f32_e32 v80, 0, v80
	v_max_f32_e32 v85, 0, v85
	v_max_f32_e32 v81, 0, v81
	v_max_f32_e32 v86, 0, v86
	v_max_f32_e32 v82, 0, v82
	v_max_f32_e32 v87, 0, v87
	v_max_f32_e32 v83, 0, v83
	v_max_f32_e32 v92, 0, v92
	v_mul_f32_e32 v95, v88, v88
	v_mul_f32_e32 v91, v89, v89
	v_lshl_add_u64 v[88:89], s[28:29], 0, v[96:97]
	v_mul_f32_e32 v84, v84, v84
	v_mul_f32_e32 v80, v80, v80
	v_mul_f32_e32 v85, v85, v85
	v_mul_f32_e32 v81, v81, v81
	v_mul_f32_e32 v86, v86, v86
	v_mul_f32_e32 v82, v82, v82
	v_mul_f32_e32 v87, v87, v87
	v_mul_f32_e32 v83, v83, v83
	v_max_f32_e32 v72, v72, v72
	v_mul_f32_e32 v98, v92, v92
	v_lshl_add_u64 v[92:93], v[88:89], 0, v[120:121]
	v_cvt_pk_bf16_f32 v83, v82, v83
	v_cvt_pk_bf16_f32 v82, v80, v81
	v_cvt_pk_bf16_f32 v81, v86, v87
	v_cvt_pk_bf16_f32 v80, v84, v85
	v_max_f32_e32 v72, 0, v72
	global_store_dwordx4 v[92:93], v[80:83], off offset:256
	v_max_f32_e32 v73, v73, v73
	v_max_f32_e32 v73, 0, v73
	v_mul_f32_e32 v83, v72, v72
	v_max_f32_e32 v72, v77, v77
	v_max_f32_e32 v72, 0, v72
	v_mul_f32_e32 v84, v72, v72
	v_mul_f32_e32 v85, v73, v73
	v_max_f32_e32 v72, v78, v78
	v_max_f32_e32 v73, v74, v74
	v_or_b32_e32 v80, 48, v148
	v_max_f32_e32 v72, 0, v72
	v_max_f32_e32 v73, 0, v73
	v_ashrrev_i32_e32 v81, 31, v80
	v_mul_f32_e32 v78, v72, v72
	v_mul_f32_e32 v74, v73, v73
	v_max_f32_e32 v72, v79, v79
	v_max_f32_e32 v73, v75, v75
	v_max_f32_e32 v68, v68, v68
	v_max_f32_e32 v64, v64, v64
	v_max_f32_e32 v69, v69, v69
	v_max_f32_e32 v65, v65, v65
	v_max_f32_e32 v70, v70, v70
	v_max_f32_e32 v66, v66, v66
	v_max_f32_e32 v71, v71, v71
	v_max_f32_e32 v67, v67, v67
	v_lshlrev_b64 v[80:81], 14, v[80:81]
	v_max_f32_e32 v76, v76, v76
	v_max_f32_e32 v72, 0, v72
	v_max_f32_e32 v73, 0, v73
	v_max_f32_e32 v68, 0, v68
	v_max_f32_e32 v64, 0, v64
	v_max_f32_e32 v69, 0, v69
	v_max_f32_e32 v65, 0, v65
	v_max_f32_e32 v70, 0, v70
	v_max_f32_e32 v66, 0, v66
	v_max_f32_e32 v71, 0, v71
	v_max_f32_e32 v67, 0, v67
	v_max_f32_e32 v76, 0, v76
	v_mul_f32_e32 v79, v72, v72
	v_mul_f32_e32 v75, v73, v73
	v_lshl_add_u64 v[72:73], s[28:29], 0, v[80:81]
	v_mul_f32_e32 v68, v68, v68
	v_mul_f32_e32 v64, v64, v64
	v_mul_f32_e32 v69, v69, v69
	v_mul_f32_e32 v65, v65, v65
	v_mul_f32_e32 v70, v70, v70
	v_mul_f32_e32 v66, v66, v66
	v_mul_f32_e32 v71, v71, v71
	v_mul_f32_e32 v67, v67, v67
	v_max_f32_e32 v56, v56, v56
	v_mul_f32_e32 v82, v76, v76
	v_lshl_add_u64 v[76:77], v[72:73], 0, v[120:121]
	v_cvt_pk_bf16_f32 v67, v66, v67
	v_cvt_pk_bf16_f32 v66, v64, v65
	v_cvt_pk_bf16_f32 v65, v70, v71
	v_cvt_pk_bf16_f32 v64, v68, v69
	v_max_f32_e32 v56, 0, v56
	global_store_dwordx4 v[76:77], v[64:67], off offset:256
	v_max_f32_e32 v57, v57, v57
	v_max_f32_e32 v57, 0, v57
	v_mul_f32_e32 v67, v56, v56
	v_max_f32_e32 v56, v61, v61
	v_max_f32_e32 v56, 0, v56
	v_mul_f32_e32 v68, v56, v56
	v_mul_f32_e32 v69, v57, v57
	v_max_f32_e32 v56, v62, v62
	v_max_f32_e32 v57, v58, v58
	v_add_u32_e32 v64, 0x80, v148
	v_max_f32_e32 v56, 0, v56
	v_max_f32_e32 v57, 0, v57
	v_ashrrev_i32_e32 v65, 31, v64
	v_mul_f32_e32 v62, v56, v56
	v_mul_f32_e32 v58, v57, v57
	v_max_f32_e32 v56, v63, v63
	v_max_f32_e32 v57, v59, v59
	v_max_f32_e32 v52, v52, v52
	v_max_f32_e32 v48, v48, v48
	v_max_f32_e32 v53, v53, v53
	v_max_f32_e32 v49, v49, v49
	v_max_f32_e32 v54, v54, v54
	v_max_f32_e32 v50, v50, v50
	v_max_f32_e32 v55, v55, v55
	v_max_f32_e32 v51, v51, v51
	v_lshlrev_b64 v[64:65], 14, v[64:65]
	v_max_f32_e32 v60, v60, v60
	v_max_f32_e32 v56, 0, v56
	v_max_f32_e32 v57, 0, v57
	v_max_f32_e32 v52, 0, v52
	v_max_f32_e32 v48, 0, v48
	v_max_f32_e32 v53, 0, v53
	v_max_f32_e32 v49, 0, v49
	v_max_f32_e32 v54, 0, v54
	v_max_f32_e32 v50, 0, v50
	v_max_f32_e32 v55, 0, v55
	v_max_f32_e32 v51, 0, v51
	v_max_f32_e32 v60, 0, v60
	v_mul_f32_e32 v63, v56, v56
	v_mul_f32_e32 v59, v57, v57
	v_lshl_add_u64 v[56:57], s[28:29], 0, v[64:65]
	v_mul_f32_e32 v52, v52, v52
	v_mul_f32_e32 v48, v48, v48
	v_mul_f32_e32 v53, v53, v53
	v_mul_f32_e32 v49, v49, v49
	v_mul_f32_e32 v54, v54, v54
	v_mul_f32_e32 v50, v50, v50
	v_mul_f32_e32 v55, v55, v55
	v_mul_f32_e32 v51, v51, v51
	v_max_f32_e32 v40, v40, v40
	v_mul_f32_e32 v66, v60, v60
	v_lshl_add_u64 v[60:61], v[56:57], 0, v[120:121]
	v_cvt_pk_bf16_f32 v51, v50, v51
	v_cvt_pk_bf16_f32 v50, v48, v49
	v_cvt_pk_bf16_f32 v49, v54, v55
	v_cvt_pk_bf16_f32 v48, v52, v53
	v_max_f32_e32 v40, 0, v40
	global_store_dwordx4 v[60:61], v[48:51], off offset:256
	v_max_f32_e32 v41, v41, v41
	v_max_f32_e32 v41, 0, v41
	v_mul_f32_e32 v51, v40, v40
	v_max_f32_e32 v40, v45, v45
	v_max_f32_e32 v40, 0, v40
	v_mul_f32_e32 v52, v40, v40
	v_mul_f32_e32 v53, v41, v41
	v_max_f32_e32 v40, v46, v46
	v_max_f32_e32 v41, v42, v42
	v_add_u32_e32 v48, 0x90, v148
	v_max_f32_e32 v40, 0, v40
	v_max_f32_e32 v41, 0, v41
	v_ashrrev_i32_e32 v49, 31, v48
	v_mul_f32_e32 v46, v40, v40
	v_mul_f32_e32 v42, v41, v41
	v_max_f32_e32 v40, v47, v47
	v_max_f32_e32 v41, v43, v43
	v_max_f32_e32 v36, v36, v36
	v_max_f32_e32 v32, v32, v32
	v_max_f32_e32 v37, v37, v37
	v_max_f32_e32 v33, v33, v33
	v_max_f32_e32 v38, v38, v38
	v_max_f32_e32 v34, v34, v34
	v_max_f32_e32 v39, v39, v39
	v_max_f32_e32 v35, v35, v35
	v_lshlrev_b64 v[48:49], 14, v[48:49]
	v_max_f32_e32 v44, v44, v44
	v_max_f32_e32 v40, 0, v40
	v_max_f32_e32 v41, 0, v41
	v_max_f32_e32 v36, 0, v36
	v_max_f32_e32 v32, 0, v32
	v_max_f32_e32 v37, 0, v37
	v_max_f32_e32 v33, 0, v33
	v_max_f32_e32 v38, 0, v38
	v_max_f32_e32 v34, 0, v34
	v_max_f32_e32 v39, 0, v39
	v_max_f32_e32 v35, 0, v35
	v_max_f32_e32 v44, 0, v44
	v_mul_f32_e32 v47, v40, v40
	v_mul_f32_e32 v43, v41, v41
	v_lshl_add_u64 v[40:41], s[28:29], 0, v[48:49]
	v_mul_f32_e32 v36, v36, v36
	v_mul_f32_e32 v32, v32, v32
	v_mul_f32_e32 v37, v37, v37
	v_mul_f32_e32 v33, v33, v33
	v_mul_f32_e32 v38, v38, v38
	v_mul_f32_e32 v34, v34, v34
	v_mul_f32_e32 v39, v39, v39
	v_mul_f32_e32 v35, v35, v35
	v_max_f32_e32 v24, v24, v24
	v_mul_f32_e32 v50, v44, v44
	v_lshl_add_u64 v[44:45], v[40:41], 0, v[120:121]
	v_cvt_pk_bf16_f32 v35, v34, v35
	v_cvt_pk_bf16_f32 v34, v32, v33
	v_cvt_pk_bf16_f32 v33, v38, v39
	v_cvt_pk_bf16_f32 v32, v36, v37
	v_max_f32_e32 v24, 0, v24
	global_store_dwordx4 v[44:45], v[32:35], off offset:256
	v_max_f32_e32 v25, v25, v25
	v_max_f32_e32 v25, 0, v25
	v_mul_f32_e32 v35, v24, v24
	v_max_f32_e32 v24, v29, v29
	v_max_f32_e32 v24, 0, v24
	v_mul_f32_e32 v36, v24, v24
	v_mul_f32_e32 v37, v25, v25
	v_max_f32_e32 v24, v30, v30
	v_max_f32_e32 v25, v26, v26
	v_add_u32_e32 v32, 0xa0, v148
	v_max_f32_e32 v24, 0, v24
	v_max_f32_e32 v25, 0, v25
	v_ashrrev_i32_e32 v33, 31, v32
	v_mul_f32_e32 v30, v24, v24
	v_mul_f32_e32 v26, v25, v25
	v_max_f32_e32 v24, v31, v31
	v_max_f32_e32 v25, v27, v27
	v_max_f32_e32 v20, v20, v20
	v_max_f32_e32 v16, v16, v16
	v_max_f32_e32 v21, v21, v21
	v_max_f32_e32 v17, v17, v17
	v_max_f32_e32 v22, v22, v22
	v_max_f32_e32 v18, v18, v18
	v_max_f32_e32 v23, v23, v23
	v_max_f32_e32 v19, v19, v19
	v_lshlrev_b64 v[32:33], 14, v[32:33]
	v_max_f32_e32 v28, v28, v28
	v_max_f32_e32 v24, 0, v24
	v_max_f32_e32 v25, 0, v25
	v_max_f32_e32 v20, 0, v20
	v_max_f32_e32 v16, 0, v16
	v_max_f32_e32 v21, 0, v21
	v_max_f32_e32 v17, 0, v17
	v_max_f32_e32 v22, 0, v22
	v_max_f32_e32 v18, 0, v18
	v_max_f32_e32 v23, 0, v23
	v_max_f32_e32 v19, 0, v19
	v_max_f32_e32 v28, 0, v28
	v_mul_f32_e32 v31, v24, v24
	v_mul_f32_e32 v27, v25, v25
	v_lshl_add_u64 v[24:25], s[28:29], 0, v[32:33]
	v_mul_f32_e32 v20, v20, v20
	v_mul_f32_e32 v16, v16, v16
	v_mul_f32_e32 v21, v21, v21
	v_mul_f32_e32 v17, v17, v17
	v_mul_f32_e32 v22, v22, v22
	v_mul_f32_e32 v18, v18, v18
	v_mul_f32_e32 v23, v23, v23
	v_mul_f32_e32 v19, v19, v19
	v_max_f32_e32 v8, v8, v8
	v_mul_f32_e32 v34, v28, v28
	v_lshl_add_u64 v[28:29], v[24:25], 0, v[120:121]
	v_cvt_pk_bf16_f32 v19, v18, v19
	v_cvt_pk_bf16_f32 v18, v16, v17
	v_cvt_pk_bf16_f32 v17, v22, v23
	v_cvt_pk_bf16_f32 v16, v20, v21
	v_max_f32_e32 v8, 0, v8
	global_store_dwordx4 v[28:29], v[16:19], off offset:256
	v_max_f32_e32 v9, v9, v9
	v_max_f32_e32 v9, 0, v9
	v_mul_f32_e32 v19, v8, v8
	v_max_f32_e32 v8, v13, v13
	v_max_f32_e32 v8, 0, v8
	v_mul_f32_e32 v20, v8, v8
	v_mul_f32_e32 v21, v9, v9
	v_max_f32_e32 v8, v14, v14
	v_max_f32_e32 v9, v10, v10
	v_add_u32_e32 v16, 0xb0, v148
	v_max_f32_e32 v8, 0, v8
	v_max_f32_e32 v9, 0, v9
	v_ashrrev_i32_e32 v17, 31, v16
	v_max_f32_e32 v12, v12, v12
	v_mul_f32_e32 v14, v8, v8
	v_mul_f32_e32 v10, v9, v9
	v_max_f32_e32 v8, v15, v15
	v_max_f32_e32 v9, v11, v11
	v_max_f32_e32 v4, v4, v4
	v_max_f32_e32 v0, v0, v0
	v_max_f32_e32 v5, v5, v5
	v_max_f32_e32 v1, v1, v1
	v_max_f32_e32 v6, v6, v6
	v_max_f32_e32 v2, v2, v2
	v_max_f32_e32 v7, v7, v7
	v_max_f32_e32 v3, v3, v3
	v_lshlrev_b64 v[16:17], 14, v[16:17]
	v_max_f32_e32 v12, 0, v12
	v_max_f32_e32 v8, 0, v8
	v_max_f32_e32 v9, 0, v9
	v_max_f32_e32 v4, 0, v4
	v_max_f32_e32 v0, 0, v0
	v_max_f32_e32 v5, 0, v5
	v_max_f32_e32 v1, 0, v1
	v_max_f32_e32 v6, 0, v6
	v_max_f32_e32 v2, 0, v2
	v_max_f32_e32 v7, 0, v7
	v_max_f32_e32 v3, 0, v3
	v_mul_f32_e32 v18, v12, v12
	v_mul_f32_e32 v15, v8, v8
	v_mul_f32_e32 v11, v9, v9
	v_lshl_add_u64 v[8:9], s[28:29], 0, v[16:17]
	v_mul_f32_e32 v4, v4, v4
	v_mul_f32_e32 v0, v0, v0
	v_mul_f32_e32 v5, v5, v5
	v_mul_f32_e32 v1, v1, v1
	v_mul_f32_e32 v6, v6, v6
	v_mul_f32_e32 v2, v2, v2
	v_mul_f32_e32 v7, v7, v7
	v_mul_f32_e32 v3, v3, v3
	v_cvt_pk_bf16_f32 v125, v125, v163
	v_cvt_pk_bf16_f32 v124, v124, v160
	v_cvt_pk_bf16_f32 v123, v161, v162
	v_cvt_pk_bf16_f32 v122, v149, v155
	v_cvt_pk_bf16_f32 v107, v106, v107
	v_cvt_pk_bf16_f32 v106, v115, v117
	v_cvt_pk_bf16_f32 v105, v110, v111
	v_cvt_pk_bf16_f32 v104, v114, v116
	v_cvt_pk_bf16_f32 v91, v90, v91
	v_cvt_pk_bf16_f32 v90, v99, v101
	v_cvt_pk_bf16_f32 v89, v94, v95
	v_cvt_pk_bf16_f32 v88, v98, v100
	v_cvt_pk_bf16_f32 v75, v74, v75
	v_cvt_pk_bf16_f32 v74, v83, v85
	v_cvt_pk_bf16_f32 v73, v78, v79
	v_cvt_pk_bf16_f32 v72, v82, v84
	v_cvt_pk_bf16_f32 v59, v58, v59
	v_cvt_pk_bf16_f32 v58, v67, v69
	v_cvt_pk_bf16_f32 v57, v62, v63
	v_cvt_pk_bf16_f32 v56, v66, v68
	v_cvt_pk_bf16_f32 v43, v42, v43
	v_cvt_pk_bf16_f32 v42, v51, v53
	v_cvt_pk_bf16_f32 v41, v46, v47
	v_cvt_pk_bf16_f32 v40, v50, v52
	v_cvt_pk_bf16_f32 v27, v26, v27
	v_cvt_pk_bf16_f32 v26, v35, v37
	v_cvt_pk_bf16_f32 v25, v30, v31
	v_cvt_pk_bf16_f32 v24, v34, v36
	v_lshl_add_u64 v[12:13], v[8:9], 0, v[120:121]
	v_cvt_pk_bf16_f32 v11, v10, v11
	v_cvt_pk_bf16_f32 v10, v19, v21
	v_cvt_pk_bf16_f32 v9, v14, v15
	v_cvt_pk_bf16_f32 v8, v18, v20
	v_cvt_pk_bf16_f32 v3, v2, v3
	v_cvt_pk_bf16_f32 v2, v0, v1
	v_cvt_pk_bf16_f32 v1, v6, v7
	v_cvt_pk_bf16_f32 v0, v4, v5
	global_store_dwordx4 v[126:127], v[122:125], off
	global_store_dwordx4 v[108:109], v[104:107], off
	global_store_dwordx4 v[92:93], v[88:91], off
	global_store_dwordx4 v[76:77], v[72:75], off
	global_store_dwordx4 v[60:61], v[56:59], off
	global_store_dwordx4 v[44:45], v[40:43], off
	global_store_dwordx4 v[28:29], v[24:27], off
	global_store_dwordx4 v[12:13], v[8:11], off
	global_store_dwordx4 v[12:13], v[0:3], off offset:256
.Ldup_nl_mlpin0:
	s_cmp_gt_u32 s58, 29
	s_barrier
	s_cbranch_scc0 .LBB0_999
	s_cmpk_gt_u32 s12, 0xff
	s_cbranch_scc1 .Ldup_done_mlpin0
	v_lshl_add_u32 v148, s44, 8, v147
	v_max_f32_e32 v124, v124, v124
	v_max_f32_e32 v120, v120, v120
	v_ashrrev_i32_e32 v149, 31, v148
	v_max_f32_e32 v124, 0, v124
	v_max_f32_e32 v120, 0, v120
	v_lshlrev_b64 v[158:159], 14, v[148:149]
	v_mul_f32_e32 v149, v124, v124
	v_mul_f32_e32 v124, v120, v120
	v_max_f32_e32 v120, v125, v125
	v_max_f32_e32 v121, v121, v121
	v_max_f32_e32 v120, 0, v120
	v_max_f32_e32 v121, 0, v121
	v_mul_f32_e32 v155, v120, v120
	v_mul_f32_e32 v160, v121, v121
	v_max_f32_e32 v120, v126, v126
	v_max_f32_e32 v121, v122, v122
	v_max_f32_e32 v120, 0, v120
	v_max_f32_e32 v121, 0, v121
	v_lshl_or_b32 v156, s33, 8, v151
	v_mul_f32_e32 v161, v120, v120
	v_mul_f32_e32 v125, v121, v121
	v_max_f32_e32 v120, v127, v127
	v_max_f32_e32 v121, v123, v123
	v_max_f32_e32 v116, v116, v116
	v_max_f32_e32 v112, v112, v112
	v_max_f32_e32 v117, v117, v117
	v_max_f32_e32 v113, v113, v113
	v_max_f32_e32 v118, v118, v118
	v_max_f32_e32 v114, v114, v114
	v_max_f32_e32 v119, v119, v119
	v_max_f32_e32 v115, v115, v115
	v_ashrrev_i32_e32 v157, 31, v156
	v_max_f32_e32 v120, 0, v120
	v_max_f32_e32 v121, 0, v121
	v_max_f32_e32 v116, 0, v116
	v_max_f32_e32 v112, 0, v112
	v_max_f32_e32 v117, 0, v117
	v_max_f32_e32 v113, 0, v113
	v_max_f32_e32 v118, 0, v118
	v_max_f32_e32 v114, 0, v114
	v_max_f32_e32 v119, 0, v119
	v_max_f32_e32 v115, 0, v115
	v_mul_f32_e32 v162, v120, v120
	v_mul_f32_e32 v163, v121, v121
	v_lshl_add_u64 v[122:123], s[28:29], 0, v[158:159]
	v_lshlrev_b64 v[120:121], 1, v[156:157]
	v_mul_f32_e32 v116, v116, v116
	v_mul_f32_e32 v112, v112, v112
	v_mul_f32_e32 v117, v117, v117
	v_mul_f32_e32 v113, v113, v113
	v_mul_f32_e32 v118, v118, v118
	v_mul_f32_e32 v114, v114, v114
	v_mul_f32_e32 v119, v119, v119
	v_mul_f32_e32 v115, v115, v115
	v_max_f32_e32 v104, v104, v104
	v_lshl_add_u64 v[126:127], v[122:123], 0, v[120:121]
	v_cvt_pk_bf16_f32 v115, v114, v115
	v_cvt_pk_bf16_f32 v114, v112, v113
	v_cvt_pk_bf16_f32 v113, v118, v119
	v_cvt_pk_bf16_f32 v112, v116, v117
	v_max_f32_e32 v104, 0, v104
	global_store_dwordx4 v[126:127], v[112:115], off offset:256
	v_max_f32_e32 v105, v105, v105
	v_max_f32_e32 v105, 0, v105
	v_mul_f32_e32 v115, v104, v104
	v_max_f32_e32 v104, v109, v109
	v_max_f32_e32 v104, 0, v104
	v_mul_f32_e32 v116, v104, v104
	v_mul_f32_e32 v117, v105, v105
	v_max_f32_e32 v104, v110, v110
	v_max_f32_e32 v105, v106, v106
	v_or_b32_e32 v112, 16, v148
	v_max_f32_e32 v104, 0, v104
	v_max_f32_e32 v105, 0, v105
	v_ashrrev_i32_e32 v113, 31, v112
	v_mul_f32_e32 v110, v104, v104
	v_mul_f32_e32 v106, v105, v105
	v_max_f32_e32 v104, v111, v111
	v_max_f32_e32 v105, v107, v107
	v_max_f32_e32 v100, v100, v100
	v_max_f32_e32 v96, v96, v96
	v_max_f32_e32 v101, v101, v101
	v_max_f32_e32 v97, v97, v97
	v_max_f32_e32 v102, v102, v102
	v_max_f32_e32 v98, v98, v98
	v_max_f32_e32 v103, v103, v103
	v_max_f32_e32 v99, v99, v99
	v_lshlrev_b64 v[112:113], 14, v[112:113]
	v_max_f32_e32 v108, v108, v108
	v_max_f32_e32 v104, 0, v104
	v_max_f32_e32 v105, 0, v105
	v_max_f32_e32 v100, 0, v100
	v_max_f32_e32 v96, 0, v96
	v_max_f32_e32 v101, 0, v101
	v_max_f32_e32 v97, 0, v97
	v_max_f32_e32 v102, 0, v102
	v_max_f32_e32 v98, 0, v98
	v_max_f32_e32 v103, 0, v103
	v_max_f32_e32 v99, 0, v99
	v_max_f32_e32 v108, 0, v108
	v_mul_f32_e32 v111, v104, v104
	v_mul_f32_e32 v107, v105, v105
	v_lshl_add_u64 v[104:105], s[28:29], 0, v[112:113]
	v_mul_f32_e32 v100, v100, v100
	v_mul_f32_e32 v96, v96, v96
	v_mul_f32_e32 v101, v101, v101
	v_mul_f32_e32 v97, v97, v97
	v_mul_f32_e32 v102, v102, v102
	v_mul_f32_e32 v98, v98, v98
	v_mul_f32_e32 v103, v103, v103
	v_mul_f32_e32 v99, v99, v99
	v_max_f32_e32 v88, v88, v88
	v_mul_f32_e32 v114, v108, v108
	v_lshl_add_u64 v[108:109], v[104:105], 0, v[120:121]
	v_cvt_pk_bf16_f32 v99, v98, v99
	v_cvt_pk_bf16_f32 v98, v96, v97
	v_cvt_pk_bf16_f32 v97, v102, v103
	v_cvt_pk_bf16_f32 v96, v100, v101
	v_max_f32_e32 v88, 0, v88
	global_store_dwordx4 v[108:109], v[96:99], off offset:256
	v_max_f32_e32 v89, v89, v89
	v_max_f32_e32 v89, 0, v89
	v_mul_f32_e32 v99, v88, v88
	v_max_f32_e32 v88, v93, v93
	v_max_f32_e32 v88, 0, v88
	v_mul_f32_e32 v100, v88, v88
	v_mul_f32_e32 v101, v89, v89
	v_max_f32_e32 v88, v94, v94
	v_max_f32_e32 v89, v90, v90
	v_or_b32_e32 v96, 32, v148
	v_max_f32_e32 v88, 0, v88
	v_max_f32_e32 v89, 0, v89
	v_ashrrev_i32_e32 v97, 31, v96
	v_mul_f32_e32 v94, v88, v88
	v_mul_f32_e32 v90, v89, v89
	v_max_f32_e32 v88, v95, v95
	v_max_f32_e32 v89, v91, v91
	v_max_f32_e32 v84, v84, v84
	v_max_f32_e32 v80, v80, v80
	v_max_f32_e32 v85, v85, v85
	v_max_f32_e32 v81, v81, v81
	v_max_f32_e32 v86, v86, v86
	v_max_f32_e32 v82, v82, v82
	v_max_f32_e32 v87, v87, v87
	v_max_f32_e32 v83, v83, v83
	v_lshlrev_b64 v[96:97], 14, v[96:97]
	v_max_f32_e32 v92, v92, v92
	v_max_f32_e32 v88, 0, v88
	v_max_f32_e32 v89, 0, v89
	v_max_f32_e32 v84, 0, v84
	v_max_f32_e32 v80, 0, v80
	v_max_f32_e32 v85, 0, v85
	v_max_f32_e32 v81, 0, v81
	v_max_f32_e32 v86, 0, v86
	v_max_f32_e32 v82, 0, v82
	v_max_f32_e32 v87, 0, v87
	v_max_f32_e32 v83, 0, v83
	v_max_f32_e32 v92, 0, v92
	v_mul_f32_e32 v95, v88, v88
	v_mul_f32_e32 v91, v89, v89
	v_lshl_add_u64 v[88:89], s[28:29], 0, v[96:97]
	v_mul_f32_e32 v84, v84, v84
	v_mul_f32_e32 v80, v80, v80
	v_mul_f32_e32 v85, v85, v85
	v_mul_f32_e32 v81, v81, v81
	v_mul_f32_e32 v86, v86, v86
	v_mul_f32_e32 v82, v82, v82
	v_mul_f32_e32 v87, v87, v87
	v_mul_f32_e32 v83, v83, v83
	v_max_f32_e32 v72, v72, v72
	v_mul_f32_e32 v98, v92, v92
	v_lshl_add_u64 v[92:93], v[88:89], 0, v[120:121]
	v_cvt_pk_bf16_f32 v83, v82, v83
	v_cvt_pk_bf16_f32 v82, v80, v81
	v_cvt_pk_bf16_f32 v81, v86, v87
	v_cvt_pk_bf16_f32 v80, v84, v85
	v_max_f32_e32 v72, 0, v72
	global_store_dwordx4 v[92:93], v[80:83], off offset:256
	v_max_f32_e32 v73, v73, v73
	v_max_f32_e32 v73, 0, v73
	v_mul_f32_e32 v83, v72, v72
	v_max_f32_e32 v72, v77, v77
	v_max_f32_e32 v72, 0, v72
	v_mul_f32_e32 v84, v72, v72
	v_mul_f32_e32 v85, v73, v73
	v_max_f32_e32 v72, v78, v78
	v_max_f32_e32 v73, v74, v74
	v_or_b32_e32 v80, 48, v148
	v_max_f32_e32 v72, 0, v72
	v_max_f32_e32 v73, 0, v73
	v_ashrrev_i32_e32 v81, 31, v80
	v_mul_f32_e32 v78, v72, v72
	v_mul_f32_e32 v74, v73, v73
	v_max_f32_e32 v72, v79, v79
	v_max_f32_e32 v73, v75, v75
	v_max_f32_e32 v68, v68, v68
	v_max_f32_e32 v64, v64, v64
	v_max_f32_e32 v69, v69, v69
	v_max_f32_e32 v65, v65, v65
	v_max_f32_e32 v70, v70, v70
	v_max_f32_e32 v66, v66, v66
	v_max_f32_e32 v71, v71, v71
	v_max_f32_e32 v67, v67, v67
	v_lshlrev_b64 v[80:81], 14, v[80:81]
	v_max_f32_e32 v76, v76, v76
	v_max_f32_e32 v72, 0, v72
	v_max_f32_e32 v73, 0, v73
	v_max_f32_e32 v68, 0, v68
	v_max_f32_e32 v64, 0, v64
	v_max_f32_e32 v69, 0, v69
	v_max_f32_e32 v65, 0, v65
	v_max_f32_e32 v70, 0, v70
	v_max_f32_e32 v66, 0, v66
	v_max_f32_e32 v71, 0, v71
	v_max_f32_e32 v67, 0, v67
	v_max_f32_e32 v76, 0, v76
	v_mul_f32_e32 v79, v72, v72
	v_mul_f32_e32 v75, v73, v73
	v_lshl_add_u64 v[72:73], s[28:29], 0, v[80:81]
	v_mul_f32_e32 v68, v68, v68
	v_mul_f32_e32 v64, v64, v64
	v_mul_f32_e32 v69, v69, v69
	v_mul_f32_e32 v65, v65, v65
	v_mul_f32_e32 v70, v70, v70
	v_mul_f32_e32 v66, v66, v66
	v_mul_f32_e32 v71, v71, v71
	v_mul_f32_e32 v67, v67, v67
	v_max_f32_e32 v56, v56, v56
	v_mul_f32_e32 v82, v76, v76
	v_lshl_add_u64 v[76:77], v[72:73], 0, v[120:121]
	v_cvt_pk_bf16_f32 v67, v66, v67
	v_cvt_pk_bf16_f32 v66, v64, v65
	v_cvt_pk_bf16_f32 v65, v70, v71
	v_cvt_pk_bf16_f32 v64, v68, v69
	v_max_f32_e32 v56, 0, v56
	global_store_dwordx4 v[76:77], v[64:67], off offset:256
	v_max_f32_e32 v57, v57, v57
	v_max_f32_e32 v57, 0, v57
	v_mul_f32_e32 v67, v56, v56
	v_max_f32_e32 v56, v61, v61
	v_max_f32_e32 v56, 0, v56
	v_mul_f32_e32 v68, v56, v56
	v_mul_f32_e32 v69, v57, v57
	v_max_f32_e32 v56, v62, v62
	v_max_f32_e32 v57, v58, v58
	v_add_u32_e32 v64, 0x80, v148
	v_max_f32_e32 v56, 0, v56
	v_max_f32_e32 v57, 0, v57
	v_ashrrev_i32_e32 v65, 31, v64
	v_mul_f32_e32 v62, v56, v56
	v_mul_f32_e32 v58, v57, v57
	v_max_f32_e32 v56, v63, v63
	v_max_f32_e32 v57, v59, v59
	v_max_f32_e32 v52, v52, v52
	v_max_f32_e32 v48, v48, v48
	v_max_f32_e32 v53, v53, v53
	v_max_f32_e32 v49, v49, v49
	v_max_f32_e32 v54, v54, v54
	v_max_f32_e32 v50, v50, v50
	v_max_f32_e32 v55, v55, v55
	v_max_f32_e32 v51, v51, v51
	v_lshlrev_b64 v[64:65], 14, v[64:65]
	v_max_f32_e32 v60, v60, v60
	v_max_f32_e32 v56, 0, v56
	v_max_f32_e32 v57, 0, v57
	v_max_f32_e32 v52, 0, v52
	v_max_f32_e32 v48, 0, v48
	v_max_f32_e32 v53, 0, v53
	v_max_f32_e32 v49, 0, v49
	v_max_f32_e32 v54, 0, v54
	v_max_f32_e32 v50, 0, v50
	v_max_f32_e32 v55, 0, v55
	v_max_f32_e32 v51, 0, v51
	v_max_f32_e32 v60, 0, v60
	v_mul_f32_e32 v63, v56, v56
	v_mul_f32_e32 v59, v57, v57
	v_lshl_add_u64 v[56:57], s[28:29], 0, v[64:65]
	v_mul_f32_e32 v52, v52, v52
	v_mul_f32_e32 v48, v48, v48
	v_mul_f32_e32 v53, v53, v53
	v_mul_f32_e32 v49, v49, v49
	v_mul_f32_e32 v54, v54, v54
	v_mul_f32_e32 v50, v50, v50
	v_mul_f32_e32 v55, v55, v55
	v_mul_f32_e32 v51, v51, v51
	v_max_f32_e32 v40, v40, v40
	v_mul_f32_e32 v66, v60, v60
	v_lshl_add_u64 v[60:61], v[56:57], 0, v[120:121]
	v_cvt_pk_bf16_f32 v51, v50, v51
	v_cvt_pk_bf16_f32 v50, v48, v49
	v_cvt_pk_bf16_f32 v49, v54, v55
	v_cvt_pk_bf16_f32 v48, v52, v53
	v_max_f32_e32 v40, 0, v40
	global_store_dwordx4 v[60:61], v[48:51], off offset:256
	v_max_f32_e32 v41, v41, v41
	v_max_f32_e32 v41, 0, v41
	v_mul_f32_e32 v51, v40, v40
	v_max_f32_e32 v40, v45, v45
	v_max_f32_e32 v40, 0, v40
	v_mul_f32_e32 v52, v40, v40
	v_mul_f32_e32 v53, v41, v41
	v_max_f32_e32 v40, v46, v46
	v_max_f32_e32 v41, v42, v42
	v_add_u32_e32 v48, 0x90, v148
	v_max_f32_e32 v40, 0, v40
	v_max_f32_e32 v41, 0, v41
	v_ashrrev_i32_e32 v49, 31, v48
	v_mul_f32_e32 v46, v40, v40
	v_mul_f32_e32 v42, v41, v41
	v_max_f32_e32 v40, v47, v47
	v_max_f32_e32 v41, v43, v43
	v_max_f32_e32 v36, v36, v36
	v_max_f32_e32 v32, v32, v32
	v_max_f32_e32 v37, v37, v37
	v_max_f32_e32 v33, v33, v33
	v_max_f32_e32 v38, v38, v38
	v_max_f32_e32 v34, v34, v34
	v_max_f32_e32 v39, v39, v39
	v_max_f32_e32 v35, v35, v35
	v_lshlrev_b64 v[48:49], 14, v[48:49]
	v_max_f32_e32 v44, v44, v44
	v_max_f32_e32 v40, 0, v40
	v_max_f32_e32 v41, 0, v41
	v_max_f32_e32 v36, 0, v36
	v_max_f32_e32 v32, 0, v32
	v_max_f32_e32 v37, 0, v37
	v_max_f32_e32 v33, 0, v33
	v_max_f32_e32 v38, 0, v38
	v_max_f32_e32 v34, 0, v34
	v_max_f32_e32 v39, 0, v39
	v_max_f32_e32 v35, 0, v35
	v_max_f32_e32 v44, 0, v44
	v_mul_f32_e32 v47, v40, v40
	v_mul_f32_e32 v43, v41, v41
	v_lshl_add_u64 v[40:41], s[28:29], 0, v[48:49]
	v_mul_f32_e32 v36, v36, v36
	v_mul_f32_e32 v32, v32, v32
	v_mul_f32_e32 v37, v37, v37
	v_mul_f32_e32 v33, v33, v33
	v_mul_f32_e32 v38, v38, v38
	v_mul_f32_e32 v34, v34, v34
	v_mul_f32_e32 v39, v39, v39
	v_mul_f32_e32 v35, v35, v35
	v_max_f32_e32 v24, v24, v24
	v_mul_f32_e32 v50, v44, v44
	v_lshl_add_u64 v[44:45], v[40:41], 0, v[120:121]
	v_cvt_pk_bf16_f32 v35, v34, v35
	v_cvt_pk_bf16_f32 v34, v32, v33
	v_cvt_pk_bf16_f32 v33, v38, v39
	v_cvt_pk_bf16_f32 v32, v36, v37
	v_max_f32_e32 v24, 0, v24
	global_store_dwordx4 v[44:45], v[32:35], off offset:256
	v_max_f32_e32 v25, v25, v25
	v_max_f32_e32 v25, 0, v25
	v_mul_f32_e32 v35, v24, v24
	v_max_f32_e32 v24, v29, v29
	v_max_f32_e32 v24, 0, v24
	v_mul_f32_e32 v36, v24, v24
	v_mul_f32_e32 v37, v25, v25
	v_max_f32_e32 v24, v30, v30
	v_max_f32_e32 v25, v26, v26
	v_add_u32_e32 v32, 0xa0, v148
	v_max_f32_e32 v24, 0, v24
	v_max_f32_e32 v25, 0, v25
	v_ashrrev_i32_e32 v33, 31, v32
	v_mul_f32_e32 v30, v24, v24
	v_mul_f32_e32 v26, v25, v25
	v_max_f32_e32 v24, v31, v31
	v_max_f32_e32 v25, v27, v27
	v_max_f32_e32 v20, v20, v20
	v_max_f32_e32 v16, v16, v16
	v_max_f32_e32 v21, v21, v21
	v_max_f32_e32 v17, v17, v17
	v_max_f32_e32 v22, v22, v22
	v_max_f32_e32 v18, v18, v18
	v_max_f32_e32 v23, v23, v23
	v_max_f32_e32 v19, v19, v19
	v_lshlrev_b64 v[32:33], 14, v[32:33]
	v_max_f32_e32 v28, v28, v28
	v_max_f32_e32 v24, 0, v24
	v_max_f32_e32 v25, 0, v25
	v_max_f32_e32 v20, 0, v20
	v_max_f32_e32 v16, 0, v16
	v_max_f32_e32 v21, 0, v21
	v_max_f32_e32 v17, 0, v17
	v_max_f32_e32 v22, 0, v22
	v_max_f32_e32 v18, 0, v18
	v_max_f32_e32 v23, 0, v23
	v_max_f32_e32 v19, 0, v19
	v_max_f32_e32 v28, 0, v28
	v_mul_f32_e32 v31, v24, v24
	v_mul_f32_e32 v27, v25, v25
	v_lshl_add_u64 v[24:25], s[28:29], 0, v[32:33]
	v_mul_f32_e32 v20, v20, v20
	v_mul_f32_e32 v16, v16, v16
	v_mul_f32_e32 v21, v21, v21
	v_mul_f32_e32 v17, v17, v17
	v_mul_f32_e32 v22, v22, v22
	v_mul_f32_e32 v18, v18, v18
	v_mul_f32_e32 v23, v23, v23
	v_mul_f32_e32 v19, v19, v19
	v_max_f32_e32 v8, v8, v8
	v_mul_f32_e32 v34, v28, v28
	v_lshl_add_u64 v[28:29], v[24:25], 0, v[120:121]
	v_cvt_pk_bf16_f32 v19, v18, v19
	v_cvt_pk_bf16_f32 v18, v16, v17
	v_cvt_pk_bf16_f32 v17, v22, v23
	v_cvt_pk_bf16_f32 v16, v20, v21
	v_max_f32_e32 v8, 0, v8
	global_store_dwordx4 v[28:29], v[16:19], off offset:256
	v_max_f32_e32 v9, v9, v9
	v_max_f32_e32 v9, 0, v9
	v_mul_f32_e32 v19, v8, v8
	v_max_f32_e32 v8, v13, v13
	v_max_f32_e32 v8, 0, v8
	v_mul_f32_e32 v20, v8, v8
	v_mul_f32_e32 v21, v9, v9
	v_max_f32_e32 v8, v14, v14
	v_max_f32_e32 v9, v10, v10
	v_add_u32_e32 v16, 0xb0, v148
	v_max_f32_e32 v8, 0, v8
	v_max_f32_e32 v9, 0, v9
	v_ashrrev_i32_e32 v17, 31, v16
	v_max_f32_e32 v12, v12, v12
	v_mul_f32_e32 v14, v8, v8
	v_mul_f32_e32 v10, v9, v9
	v_max_f32_e32 v8, v15, v15
	v_max_f32_e32 v9, v11, v11
	v_max_f32_e32 v4, v4, v4
	v_max_f32_e32 v0, v0, v0
	v_max_f32_e32 v5, v5, v5
	v_max_f32_e32 v1, v1, v1
	v_max_f32_e32 v6, v6, v6
	v_max_f32_e32 v2, v2, v2
	v_max_f32_e32 v7, v7, v7
	v_max_f32_e32 v3, v3, v3
	v_lshlrev_b64 v[16:17], 14, v[16:17]
	v_max_f32_e32 v12, 0, v12
	v_max_f32_e32 v8, 0, v8
	v_max_f32_e32 v9, 0, v9
	v_max_f32_e32 v4, 0, v4
	v_max_f32_e32 v0, 0, v0
	v_max_f32_e32 v5, 0, v5
	v_max_f32_e32 v1, 0, v1
	v_max_f32_e32 v6, 0, v6
	v_max_f32_e32 v2, 0, v2
	v_max_f32_e32 v7, 0, v7
	v_max_f32_e32 v3, 0, v3
	v_mul_f32_e32 v18, v12, v12
	v_mul_f32_e32 v15, v8, v8
	v_mul_f32_e32 v11, v9, v9
	v_lshl_add_u64 v[8:9], s[28:29], 0, v[16:17]
	v_mul_f32_e32 v4, v4, v4
	v_mul_f32_e32 v0, v0, v0
	v_mul_f32_e32 v5, v5, v5
	v_mul_f32_e32 v1, v1, v1
	v_mul_f32_e32 v6, v6, v6
	v_mul_f32_e32 v2, v2, v2
	v_mul_f32_e32 v7, v7, v7
	v_mul_f32_e32 v3, v3, v3
	v_cvt_pk_bf16_f32 v125, v125, v163
	v_cvt_pk_bf16_f32 v124, v124, v160
	v_cvt_pk_bf16_f32 v123, v161, v162
	v_cvt_pk_bf16_f32 v122, v149, v155
	v_cvt_pk_bf16_f32 v107, v106, v107
	v_cvt_pk_bf16_f32 v106, v115, v117
	v_cvt_pk_bf16_f32 v105, v110, v111
	v_cvt_pk_bf16_f32 v104, v114, v116
	v_cvt_pk_bf16_f32 v91, v90, v91
	v_cvt_pk_bf16_f32 v90, v99, v101
	v_cvt_pk_bf16_f32 v89, v94, v95
	v_cvt_pk_bf16_f32 v88, v98, v100
	v_cvt_pk_bf16_f32 v75, v74, v75
	v_cvt_pk_bf16_f32 v74, v83, v85
	v_cvt_pk_bf16_f32 v73, v78, v79
	v_cvt_pk_bf16_f32 v72, v82, v84
	v_cvt_pk_bf16_f32 v59, v58, v59
	v_cvt_pk_bf16_f32 v58, v67, v69
	v_cvt_pk_bf16_f32 v57, v62, v63
	v_cvt_pk_bf16_f32 v56, v66, v68
	v_cvt_pk_bf16_f32 v43, v42, v43
	v_cvt_pk_bf16_f32 v42, v51, v53
	v_cvt_pk_bf16_f32 v41, v46, v47
	v_cvt_pk_bf16_f32 v40, v50, v52
	v_cvt_pk_bf16_f32 v27, v26, v27
	v_cvt_pk_bf16_f32 v26, v35, v37
	v_cvt_pk_bf16_f32 v25, v30, v31
	v_cvt_pk_bf16_f32 v24, v34, v36
	v_lshl_add_u64 v[12:13], v[8:9], 0, v[120:121]
	v_cvt_pk_bf16_f32 v11, v10, v11
	v_cvt_pk_bf16_f32 v10, v19, v21
	v_cvt_pk_bf16_f32 v9, v14, v15
	v_cvt_pk_bf16_f32 v8, v18, v20
	v_cvt_pk_bf16_f32 v3, v2, v3
	v_cvt_pk_bf16_f32 v2, v0, v1
	v_cvt_pk_bf16_f32 v1, v6, v7
	v_cvt_pk_bf16_f32 v0, v4, v5
	global_store_dwordx4 v[126:127], v[122:125], off
	global_store_dwordx4 v[108:109], v[104:107], off
	global_store_dwordx4 v[92:93], v[88:91], off
	global_store_dwordx4 v[76:77], v[72:75], off
	global_store_dwordx4 v[60:61], v[56:59], off
	global_store_dwordx4 v[44:45], v[40:43], off
	global_store_dwordx4 v[28:29], v[24:27], off
	global_store_dwordx4 v[12:13], v[8:11], off
	global_store_dwordx4 v[12:13], v[0:3], off offset:256
.Ldup_done_mlpin0:
	s_and_b64 vcc, exec, s[0:1]
	s_mov_b32 s33, s10
	s_mov_b32 s44, s14
	s_mov_b64 s[48:49], s[18:19]
	s_mov_b64 s[46:47], s[16:17]
	s_cbranch_vccz .LBB0_996
	s_waitcnt vmcnt(0)
	v_readlane_b32 s52, v254, 7
	s_cmpk_gt_u32 s12, 0xff
	v_readlane_b32 s53, v254, 8
	s_cbranch_scc1 .LBB0_1003
	s_barrier

.LBB0_1402:
	ds_read_b128 v[154:157], v151
	ds_read_b128 v[158:161], v151 offset:1024
	ds_read_b128 v[162:165], v151 offset:2048
	ds_read_b128 v[166:169], v151 offset:3072
	s_add_u32 s20, s26, 0xfff80080
	s_addc_u32 s21, s27, -1
	s_cmp_eq_u32 s52, 28
	s_cselect_b32 s21, s15, s21
	s_cselect_b32 s20, s48, s20
	s_cselect_b32 s37, s11, s51
	s_cselect_b32 s36, s49, s50
	v_lshl_add_u64 v[148:149], s[26:27], 0, v[136:137]
	s_add_i32 m0, s25, 0xc000
	ds_read_b128 v[170:173], v152
	ds_read_b128 v[174:177], v152 offset:1024
	ds_read_b128 v[178:181], v152 offset:2048
	ds_read_b128 v[182:185], v152 offset:3072
	ds_read_b128 v[186:189], v152 offset:4096
	ds_read_b128 v[196:199], v152 offset:5120
	ds_read_b128 v[200:203], v152 offset:6144
	ds_read_b128 v[204:207], v152 offset:7168
	global_load_lds_dwordx4 v[148:149], off
	v_lshl_add_u64 v[148:149], s[26:27], 0, v[138:139]
	s_add_i32 m0, s25, 0xe000
	s_nop 0
	global_load_lds_dwordx4 v[148:149], off
	s_waitcnt lgkmcnt(8)
	s_barrier
	s_waitcnt lgkmcnt(0)
	s_setprio 1
	s_waitcnt lgkmcnt(0)
	v_mfma_f32_16x16x32_bf16 v[124:127], v[154:157], v[170:173], v[124:127]
	v_mfma_f32_16x16x32_bf16 v[120:123], v[162:165], v[170:173], v[120:123]
	v_mfma_f32_16x16x32_bf16 v[108:111], v[154:157], v[178:181], v[108:111]
	v_mfma_f32_16x16x32_bf16 v[104:107], v[162:165], v[178:181], v[104:107]
	v_mfma_f32_16x16x32_bf16 v[92:95], v[154:157], v[186:189], v[92:95]
	v_mfma_f32_16x16x32_bf16 v[88:91], v[162:165], v[186:189], v[88:91]
	v_mfma_f32_16x16x32_bf16 v[76:79], v[154:157], v[200:203], v[76:79]
	v_mfma_f32_16x16x32_bf16 v[72:75], v[162:165], v[200:203], v[72:75]
	v_mfma_f32_16x16x32_bf16 v[124:127], v[158:161], v[174:177], v[124:127]
	v_mfma_f32_16x16x32_bf16 v[120:123], v[166:169], v[174:177], v[120:123]
	v_mfma_f32_16x16x32_bf16 v[108:111], v[158:161], v[182:185], v[108:111]
	v_mfma_f32_16x16x32_bf16 v[104:107], v[166:169], v[182:185], v[104:107]
	v_mfma_f32_16x16x32_bf16 v[92:95], v[158:161], v[196:199], v[92:95]
	v_mfma_f32_16x16x32_bf16 v[88:91], v[166:169], v[196:199], v[88:91]
	v_mfma_f32_16x16x32_bf16 v[76:79], v[158:161], v[204:207], v[76:79]
	v_mfma_f32_16x16x32_bf16 v[72:75], v[166:169], v[204:207], v[72:75]
	s_setprio 0
	s_barrier
	s_add_i32 s53, s46, s23
	v_lshl_add_u64 v[148:149], s[36:37], 0, v[132:133]
	s_mov_b32 m0, s53
	ds_read_b128 v[208:211], v153
	ds_read_b128 v[212:215], v153 offset:1024
	ds_read_b128 v[216:219], v153 offset:2048
	ds_read_b128 v[220:223], v153 offset:3072
	global_load_lds_dwordx4 v[148:149], off
	v_lshl_add_u64 v[190:191], s[36:37], 0, v[128:129]
	s_add_i32 m0, s53, 0x2000
	s_nop 0
	global_load_lds_dwordx4 v[190:191], off
	s_barrier
	s_waitcnt lgkmcnt(0)
	s_setprio 1
	s_waitcnt lgkmcnt(0)
	v_mfma_f32_16x16x32_bf16 v[116:119], v[208:211], v[170:173], v[116:119]
	v_mfma_f32_16x16x32_bf16 v[112:115], v[216:219], v[170:173], v[112:115]
	v_mfma_f32_16x16x32_bf16 v[100:103], v[208:211], v[178:181], v[100:103]
	v_mfma_f32_16x16x32_bf16 v[96:99], v[216:219], v[178:181], v[96:99]
	v_mfma_f32_16x16x32_bf16 v[84:87], v[208:211], v[186:189], v[84:87]
	v_mfma_f32_16x16x32_bf16 v[80:83], v[216:219], v[186:189], v[80:83]
	v_mfma_f32_16x16x32_bf16 v[68:71], v[208:211], v[200:203], v[68:71]
	v_mfma_f32_16x16x32_bf16 v[64:67], v[216:219], v[200:203], v[64:67]
	v_mfma_f32_16x16x32_bf16 v[116:119], v[212:215], v[174:177], v[116:119]
	v_mfma_f32_16x16x32_bf16 v[112:115], v[220:223], v[174:177], v[112:115]
	v_mfma_f32_16x16x32_bf16 v[100:103], v[212:215], v[182:185], v[100:103]
	v_mfma_f32_16x16x32_bf16 v[96:99], v[220:223], v[182:185], v[96:99]
	v_mfma_f32_16x16x32_bf16 v[84:87], v[212:215], v[196:199], v[84:87]
	v_mfma_f32_16x16x32_bf16 v[80:83], v[220:223], v[196:199], v[80:83]
	v_mfma_f32_16x16x32_bf16 v[68:71], v[212:215], v[204:207], v[68:71]
	v_mfma_f32_16x16x32_bf16 v[64:67], v[220:223], v[204:207], v[64:67]
	s_setprio 0
	s_mov_b32 m0, s25
	v_lshl_add_u64 v[224:225], s[20:21], 0, v[134:135]
	s_barrier
	ds_read_b128 v[170:173], v152 offset:16384
	ds_read_b128 v[174:177], v152 offset:17408
	ds_read_b128 v[178:181], v152 offset:18432
	ds_read_b128 v[182:185], v152 offset:19456
	ds_read_b128 v[186:189], v152 offset:20480
	ds_read_b128 v[196:199], v152 offset:21504
	ds_read_b128 v[200:203], v152 offset:22528
	ds_read_b128 v[204:207], v152 offset:23552
	global_load_lds_dwordx4 v[224:225], off
	v_lshl_add_u64 v[226:227], s[20:21], 0, v[130:131]
	s_mov_b32 m0, s35
	s_nop 0
	global_load_lds_dwordx4 v[226:227], off
	s_barrier
	s_waitcnt lgkmcnt(0)
	s_setprio 1
	s_waitcnt lgkmcnt(0)
	v_mfma_f32_16x16x32_bf16 v[60:63], v[154:157], v[170:173], v[60:63]
	v_mfma_f32_16x16x32_bf16 v[56:59], v[162:165], v[170:173], v[56:59]
	v_mfma_f32_16x16x32_bf16 v[44:47], v[154:157], v[178:181], v[44:47]
	v_mfma_f32_16x16x32_bf16 v[40:43], v[162:165], v[178:181], v[40:43]
	v_mfma_f32_16x16x32_bf16 v[28:31], v[154:157], v[186:189], v[28:31]
	v_mfma_f32_16x16x32_bf16 v[24:27], v[162:165], v[186:189], v[24:27]
	v_mfma_f32_16x16x32_bf16 v[12:15], v[154:157], v[200:203], v[12:15]
	v_mfma_f32_16x16x32_bf16 v[8:11], v[162:165], v[200:203], v[8:11]
	v_mfma_f32_16x16x32_bf16 v[60:63], v[158:161], v[174:177], v[60:63]
	v_mfma_f32_16x16x32_bf16 v[56:59], v[166:169], v[174:177], v[56:59]
	v_mfma_f32_16x16x32_bf16 v[44:47], v[158:161], v[182:185], v[44:47]
	v_mfma_f32_16x16x32_bf16 v[40:43], v[166:169], v[182:185], v[40:43]
	v_mfma_f32_16x16x32_bf16 v[28:31], v[158:161], v[196:199], v[28:31]
	v_mfma_f32_16x16x32_bf16 v[24:27], v[166:169], v[196:199], v[24:27]
	v_mfma_f32_16x16x32_bf16 v[12:15], v[158:161], v[204:207], v[12:15]
	v_mfma_f32_16x16x32_bf16 v[8:11], v[166:169], v[204:207], v[8:11]
	s_setprio 0
	s_barrier
	s_add_u32 s54, s36, 0x80000
	s_addc_u32 s55, s37, 0
	s_add_i32 s53, s47, s23
	v_lshl_add_u64 v[154:155], s[54:55], 0, v[132:133]
	s_mov_b32 m0, s53
	s_nop 0
	global_load_lds_dwordx4 v[154:155], off
	v_lshl_add_u64 v[154:155], s[54:55], 0, v[128:129]
	s_add_i32 m0, s53, 0x2000
	s_nop 0
	global_load_lds_dwordx4 v[154:155], off
	s_waitcnt vmcnt(6)
	s_barrier
	s_setprio 1
	v_mfma_f32_16x16x32_bf16 v[52:55], v[208:211], v[170:173], v[52:55]
	v_mfma_f32_16x16x32_bf16 v[48:51], v[216:219], v[170:173], v[48:51]
	v_mfma_f32_16x16x32_bf16 v[36:39], v[208:211], v[178:181], v[36:39]
	v_mfma_f32_16x16x32_bf16 v[32:35], v[216:219], v[178:181], v[32:35]
	v_mfma_f32_16x16x32_bf16 v[20:23], v[208:211], v[186:189], v[20:23]
	v_mfma_f32_16x16x32_bf16 v[16:19], v[216:219], v[186:189], v[16:19]
	v_mfma_f32_16x16x32_bf16 v[4:7], v[208:211], v[200:203], v[4:7]
	v_mfma_f32_16x16x32_bf16 v[0:3], v[216:219], v[200:203], v[0:3]
	v_mfma_f32_16x16x32_bf16 v[52:55], v[212:215], v[174:177], v[52:55]
	v_mfma_f32_16x16x32_bf16 v[48:51], v[220:223], v[174:177], v[48:51]
	v_mfma_f32_16x16x32_bf16 v[36:39], v[212:215], v[182:185], v[36:39]
	v_mfma_f32_16x16x32_bf16 v[32:35], v[220:223], v[182:185], v[32:35]
	v_mfma_f32_16x16x32_bf16 v[20:23], v[212:215], v[196:199], v[20:23]
	v_mfma_f32_16x16x32_bf16 v[16:19], v[220:223], v[196:199], v[16:19]
	v_mfma_f32_16x16x32_bf16 v[4:7], v[212:215], v[204:207], v[4:7]
	v_mfma_f32_16x16x32_bf16 v[0:3], v[220:223], v[204:207], v[0:3]
	s_setprio 0
	s_add_i32 s53, 0, 0x18000
	v_add_u32_e32 v166, s53, v147
	s_barrier
	ds_read_b128 v[154:157], v166
	ds_read_b128 v[158:161], v166 offset:1024
	ds_read_b128 v[162:165], v166 offset:2048
	ds_read_b128 v[166:169], v166 offset:3072
	s_add_u32 s20, s20, 0x80000
	s_addc_u32 s21, s21, 0
	s_mov_b32 m0, s38
	v_lshl_add_u64 v[208:209], s[20:21], 0, v[134:135]
	ds_read_b128 v[170:173], v152 offset:32768
	ds_read_b128 v[174:177], v152 offset:33792
	ds_read_b128 v[178:181], v152 offset:34816
	ds_read_b128 v[182:185], v152 offset:35840
	ds_read_b128 v[186:189], v152 offset:36864
	ds_read_b128 v[196:199], v152 offset:37888
	ds_read_b128 v[200:203], v152 offset:38912
	ds_read_b128 v[204:207], v152 offset:39936
	global_load_lds_dwordx4 v[208:209], off
	v_lshl_add_u64 v[208:209], s[20:21], 0, v[130:131]
	s_mov_b32 m0, s39
	s_nop 0
	global_load_lds_dwordx4 v[208:209], off
	s_waitcnt lgkmcnt(8)
	s_barrier
	s_waitcnt lgkmcnt(0)
	s_setprio 1
	s_waitcnt lgkmcnt(0)
	v_mfma_f32_16x16x32_bf16 v[124:127], v[154:157], v[170:173], v[124:127]
	v_mfma_f32_16x16x32_bf16 v[120:123], v[162:165], v[170:173], v[120:123]
	v_mfma_f32_16x16x32_bf16 v[108:111], v[154:157], v[178:181], v[108:111]
	v_mfma_f32_16x16x32_bf16 v[104:107], v[162:165], v[178:181], v[104:107]
	v_mfma_f32_16x16x32_bf16 v[92:95], v[154:157], v[186:189], v[92:95]
	v_mfma_f32_16x16x32_bf16 v[88:91], v[162:165], v[186:189], v[88:91]
	v_mfma_f32_16x16x32_bf16 v[76:79], v[154:157], v[200:203], v[76:79]
	v_mfma_f32_16x16x32_bf16 v[72:75], v[162:165], v[200:203], v[72:75]
	v_mfma_f32_16x16x32_bf16 v[124:127], v[158:161], v[174:177], v[124:127]
	v_mfma_f32_16x16x32_bf16 v[120:123], v[166:169], v[174:177], v[120:123]
	v_mfma_f32_16x16x32_bf16 v[108:111], v[158:161], v[182:185], v[108:111]
	v_mfma_f32_16x16x32_bf16 v[104:107], v[166:169], v[182:185], v[104:107]
	v_mfma_f32_16x16x32_bf16 v[92:95], v[158:161], v[196:199], v[92:95]
	v_mfma_f32_16x16x32_bf16 v[88:91], v[166:169], v[196:199], v[88:91]
	v_mfma_f32_16x16x32_bf16 v[76:79], v[158:161], v[204:207], v[76:79]
	v_mfma_f32_16x16x32_bf16 v[72:75], v[166:169], v[204:207], v[72:75]
	s_setprio 0
	s_barrier
	s_add_i32 s54, 0, 0x1c000
	s_add_i32 s20, s53, s23
	v_add_u32_e32 v193, s54, v147
	v_lshl_add_u64 v[148:149], v[148:149], 0, s[8:9]
	s_mov_b32 m0, s20
	ds_read_b128 v[208:211], v193
	ds_read_b128 v[212:215], v193 offset:1024
	ds_read_b128 v[216:219], v193 offset:2048
	ds_read_b128 v[220:223], v193 offset:3072
	global_load_lds_dwordx4 v[148:149], off
	v_lshl_add_u64 v[148:149], v[190:191], 0, s[8:9]
	s_add_i32 m0, s20, 0x2000
	s_nop 0
	global_load_lds_dwordx4 v[148:149], off
	s_barrier
	s_waitcnt lgkmcnt(0)
	s_setprio 1
	s_waitcnt lgkmcnt(0)
	v_mfma_f32_16x16x32_bf16 v[116:119], v[208:211], v[170:173], v[116:119]
	v_mfma_f32_16x16x32_bf16 v[112:115], v[216:219], v[170:173], v[112:115]
	v_mfma_f32_16x16x32_bf16 v[100:103], v[208:211], v[178:181], v[100:103]
	v_mfma_f32_16x16x32_bf16 v[96:99], v[216:219], v[178:181], v[96:99]
	v_mfma_f32_16x16x32_bf16 v[84:87], v[208:211], v[186:189], v[84:87]
	v_mfma_f32_16x16x32_bf16 v[80:83], v[216:219], v[186:189], v[80:83]
	v_mfma_f32_16x16x32_bf16 v[68:71], v[208:211], v[200:203], v[68:71]
	v_mfma_f32_16x16x32_bf16 v[64:67], v[216:219], v[200:203], v[64:67]
	v_mfma_f32_16x16x32_bf16 v[116:119], v[212:215], v[174:177], v[116:119]
	v_mfma_f32_16x16x32_bf16 v[112:115], v[220:223], v[174:177], v[112:115]
	v_mfma_f32_16x16x32_bf16 v[100:103], v[212:215], v[182:185], v[100:103]
	v_mfma_f32_16x16x32_bf16 v[96:99], v[220:223], v[182:185], v[96:99]
	v_mfma_f32_16x16x32_bf16 v[84:87], v[212:215], v[196:199], v[84:87]
	v_mfma_f32_16x16x32_bf16 v[80:83], v[220:223], v[196:199], v[80:83]
	v_mfma_f32_16x16x32_bf16 v[68:71], v[212:215], v[204:207], v[68:71]
	v_mfma_f32_16x16x32_bf16 v[64:67], v[220:223], v[204:207], v[64:67]
	s_setprio 0
	s_mov_b32 m0, s41
	v_lshl_add_u64 v[148:149], v[224:225], 0, s[8:9]
	s_barrier
	ds_read_b128 v[170:173], v152 offset:49152
	ds_read_b128 v[174:177], v152 offset:50176
	ds_read_b128 v[178:181], v152 offset:51200
	ds_read_b128 v[182:185], v152 offset:52224
	ds_read_b128 v[186:189], v152 offset:53248
	ds_read_b128 v[196:199], v152 offset:54272
	ds_read_b128 v[200:203], v152 offset:55296
	ds_read_b128 v[204:207], v152 offset:56320
	global_load_lds_dwordx4 v[148:149], off
	v_lshl_add_u64 v[148:149], v[226:227], 0, s[8:9]
	s_mov_b32 m0, s44
	s_nop 0
	global_load_lds_dwordx4 v[148:149], off
	s_barrier
	s_waitcnt lgkmcnt(0)
	s_setprio 1
	s_waitcnt lgkmcnt(0)
	v_mfma_f32_16x16x32_bf16 v[60:63], v[154:157], v[170:173], v[60:63]
	v_mfma_f32_16x16x32_bf16 v[56:59], v[162:165], v[170:173], v[56:59]
	v_mfma_f32_16x16x32_bf16 v[44:47], v[154:157], v[178:181], v[44:47]
	v_mfma_f32_16x16x32_bf16 v[40:43], v[162:165], v[178:181], v[40:43]
	v_mfma_f32_16x16x32_bf16 v[28:31], v[154:157], v[186:189], v[28:31]
	v_mfma_f32_16x16x32_bf16 v[24:27], v[162:165], v[186:189], v[24:27]
	v_mfma_f32_16x16x32_bf16 v[12:15], v[154:157], v[200:203], v[12:15]
	v_mfma_f32_16x16x32_bf16 v[8:11], v[162:165], v[200:203], v[8:11]
	v_mfma_f32_16x16x32_bf16 v[60:63], v[158:161], v[174:177], v[60:63]
	v_mfma_f32_16x16x32_bf16 v[56:59], v[166:169], v[174:177], v[56:59]
	v_mfma_f32_16x16x32_bf16 v[44:47], v[158:161], v[182:185], v[44:47]
	v_mfma_f32_16x16x32_bf16 v[40:43], v[166:169], v[182:185], v[40:43]
	v_mfma_f32_16x16x32_bf16 v[28:31], v[158:161], v[196:199], v[28:31]
	v_mfma_f32_16x16x32_bf16 v[24:27], v[166:169], v[196:199], v[24:27]
	v_mfma_f32_16x16x32_bf16 v[12:15], v[158:161], v[204:207], v[12:15]
	v_mfma_f32_16x16x32_bf16 v[8:11], v[166:169], v[204:207], v[8:11]
	s_setprio 0
	s_barrier
	s_add_u32 s20, s36, 0x80080
	s_addc_u32 s21, s37, 0
	s_add_i32 s36, s54, s23
	v_lshl_add_u64 v[148:149], s[20:21], 0, v[132:133]
	s_mov_b32 m0, s36
	s_nop 0
	global_load_lds_dwordx4 v[148:149], off
	v_lshl_add_u64 v[148:149], s[20:21], 0, v[128:129]
	s_add_i32 m0, s36, 0x2000
	s_nop 0
	global_load_lds_dwordx4 v[148:149], off
	s_waitcnt vmcnt(6)
	s_barrier
	s_setprio 1
	v_mfma_f32_16x16x32_bf16 v[52:55], v[208:211], v[170:173], v[52:55]
	v_mfma_f32_16x16x32_bf16 v[48:51], v[216:219], v[170:173], v[48:51]
	v_mfma_f32_16x16x32_bf16 v[36:39], v[208:211], v[178:181], v[36:39]
	v_mfma_f32_16x16x32_bf16 v[32:35], v[216:219], v[178:181], v[32:35]
	v_mfma_f32_16x16x32_bf16 v[20:23], v[208:211], v[186:189], v[20:23]
	v_mfma_f32_16x16x32_bf16 v[16:19], v[216:219], v[186:189], v[16:19]
	v_mfma_f32_16x16x32_bf16 v[4:7], v[208:211], v[200:203], v[4:7]
	v_mfma_f32_16x16x32_bf16 v[0:3], v[216:219], v[200:203], v[0:3]
	v_mfma_f32_16x16x32_bf16 v[52:55], v[212:215], v[174:177], v[52:55]
	v_mfma_f32_16x16x32_bf16 v[48:51], v[220:223], v[174:177], v[48:51]
	v_mfma_f32_16x16x32_bf16 v[36:39], v[212:215], v[182:185], v[36:39]
	v_mfma_f32_16x16x32_bf16 v[32:35], v[220:223], v[182:185], v[32:35]
	v_mfma_f32_16x16x32_bf16 v[20:23], v[212:215], v[196:199], v[20:23]
	v_mfma_f32_16x16x32_bf16 v[16:19], v[220:223], v[196:199], v[16:19]
	v_mfma_f32_16x16x32_bf16 v[4:7], v[212:215], v[204:207], v[4:7]
	v_mfma_f32_16x16x32_bf16 v[0:3], v[220:223], v[204:207], v[0:3]
	s_setprio 0
	s_add_i32 s52, s52, 2
	s_add_u32 s26, s26, 0x100
	s_addc_u32 s27, s27, 0
	s_add_u32 s50, s50, 0x100
	s_addc_u32 s51, s51, 0
	s_cmp_gt_u32 s52, 29
	s_cbranch_scc0 .Ldup_nl_mlpin1
	s_cmpk_gt_u32 s12, 0xff
	s_cbranch_scc0 .Ldup_nl_mlpin1
	v_lshl_add_u32 v148, s24, 8, v145
	v_max_f32_e32 v124, v124, v124
	v_max_f32_e32 v120, v120, v120
	v_ashrrev_i32_e32 v149, 31, v148
	v_max_f32_e32 v124, 0, v124
	v_max_f32_e32 v120, 0, v120
	v_lshlrev_b64 v[156:157], 14, v[148:149]
	v_mul_f32_e32 v149, v124, v124
	v_mul_f32_e32 v124, v120, v120
	v_max_f32_e32 v120, v125, v125
	v_max_f32_e32 v121, v121, v121
	v_max_f32_e32 v120, 0, v120
	v_max_f32_e32 v121, 0, v121
	v_mul_f32_e32 v158, v120, v120
	v_mul_f32_e32 v159, v121, v121
	v_max_f32_e32 v120, v126, v126
	v_max_f32_e32 v121, v122, v122
	v_max_f32_e32 v120, 0, v120
	v_max_f32_e32 v121, 0, v121
	v_lshl_or_b32 v154, s33, 8, v150
	v_mul_f32_e32 v160, v120, v120
	v_mul_f32_e32 v125, v121, v121
	v_max_f32_e32 v120, v127, v127
	v_max_f32_e32 v121, v123, v123
	v_max_f32_e32 v116, v116, v116
	v_max_f32_e32 v112, v112, v112
	v_max_f32_e32 v117, v117, v117
	v_max_f32_e32 v113, v113, v113
	v_max_f32_e32 v118, v118, v118
	v_max_f32_e32 v114, v114, v114
	v_max_f32_e32 v119, v119, v119
	v_max_f32_e32 v115, v115, v115
	v_ashrrev_i32_e32 v155, 31, v154
	v_max_f32_e32 v120, 0, v120
	v_max_f32_e32 v121, 0, v121
	v_max_f32_e32 v116, 0, v116
	v_max_f32_e32 v112, 0, v112
	v_max_f32_e32 v117, 0, v117
	v_max_f32_e32 v113, 0, v113
	v_max_f32_e32 v118, 0, v118
	v_max_f32_e32 v114, 0, v114
	v_max_f32_e32 v119, 0, v119
	v_max_f32_e32 v115, 0, v115
	v_mul_f32_e32 v161, v120, v120
	v_mul_f32_e32 v162, v121, v121
	v_lshl_add_u64 v[122:123], s[28:29], 0, v[156:157]
	v_lshlrev_b64 v[120:121], 1, v[154:155]
	v_mul_f32_e32 v116, v116, v116
	v_mul_f32_e32 v112, v112, v112
	v_mul_f32_e32 v117, v117, v117
	v_mul_f32_e32 v113, v113, v113
	v_mul_f32_e32 v118, v118, v118
	v_mul_f32_e32 v114, v114, v114
	v_mul_f32_e32 v119, v119, v119
	v_mul_f32_e32 v115, v115, v115
	v_max_f32_e32 v104, v104, v104
	v_lshl_add_u64 v[126:127], v[122:123], 0, v[120:121]
	v_cvt_pk_bf16_f32 v115, v114, v115
	v_cvt_pk_bf16_f32 v114, v112, v113
	v_cvt_pk_bf16_f32 v113, v118, v119
	v_cvt_pk_bf16_f32 v112, v116, v117
	v_max_f32_e32 v104, 0, v104
	global_store_dwordx4 v[126:127], v[112:115], off offset:256
	v_max_f32_e32 v105, v105, v105
	v_max_f32_e32 v105, 0, v105
	v_mul_f32_e32 v115, v104, v104
	v_max_f32_e32 v104, v109, v109
	v_max_f32_e32 v104, 0, v104
	v_mul_f32_e32 v116, v104, v104
	v_mul_f32_e32 v117, v105, v105
	v_max_f32_e32 v104, v110, v110
	v_max_f32_e32 v105, v106, v106
	v_or_b32_e32 v112, 16, v148
	v_max_f32_e32 v104, 0, v104
	v_max_f32_e32 v105, 0, v105
	v_ashrrev_i32_e32 v113, 31, v112
	v_mul_f32_e32 v110, v104, v104
	v_mul_f32_e32 v106, v105, v105
	v_max_f32_e32 v104, v111, v111
	v_max_f32_e32 v105, v107, v107
	v_max_f32_e32 v100, v100, v100
	v_max_f32_e32 v96, v96, v96
	v_max_f32_e32 v101, v101, v101
	v_max_f32_e32 v97, v97, v97
	v_max_f32_e32 v102, v102, v102
	v_max_f32_e32 v98, v98, v98
	v_max_f32_e32 v103, v103, v103
	v_max_f32_e32 v99, v99, v99
	v_lshlrev_b64 v[112:113], 14, v[112:113]
	v_max_f32_e32 v108, v108, v108
	v_max_f32_e32 v104, 0, v104
	v_max_f32_e32 v105, 0, v105
	v_max_f32_e32 v100, 0, v100
	v_max_f32_e32 v96, 0, v96
	v_max_f32_e32 v101, 0, v101
	v_max_f32_e32 v97, 0, v97
	v_max_f32_e32 v102, 0, v102
	v_max_f32_e32 v98, 0, v98
	v_max_f32_e32 v103, 0, v103
	v_max_f32_e32 v99, 0, v99
	v_max_f32_e32 v108, 0, v108
	v_mul_f32_e32 v111, v104, v104
	v_mul_f32_e32 v107, v105, v105
	v_lshl_add_u64 v[104:105], s[28:29], 0, v[112:113]
	v_mul_f32_e32 v100, v100, v100
	v_mul_f32_e32 v96, v96, v96
	v_mul_f32_e32 v101, v101, v101
	v_mul_f32_e32 v97, v97, v97
	v_mul_f32_e32 v102, v102, v102
	v_mul_f32_e32 v98, v98, v98
	v_mul_f32_e32 v103, v103, v103
	v_mul_f32_e32 v99, v99, v99
	v_max_f32_e32 v88, v88, v88
	v_mul_f32_e32 v114, v108, v108
	v_lshl_add_u64 v[108:109], v[104:105], 0, v[120:121]
	v_cvt_pk_bf16_f32 v99, v98, v99
	v_cvt_pk_bf16_f32 v98, v96, v97
	v_cvt_pk_bf16_f32 v97, v102, v103
	v_cvt_pk_bf16_f32 v96, v100, v101
	v_max_f32_e32 v88, 0, v88
	global_store_dwordx4 v[108:109], v[96:99], off offset:256
	v_max_f32_e32 v89, v89, v89
	v_max_f32_e32 v89, 0, v89
	v_mul_f32_e32 v99, v88, v88
	v_max_f32_e32 v88, v93, v93
	v_max_f32_e32 v88, 0, v88
	v_mul_f32_e32 v100, v88, v88
	v_mul_f32_e32 v101, v89, v89
	v_max_f32_e32 v88, v94, v94
	v_max_f32_e32 v89, v90, v90
	v_or_b32_e32 v96, 32, v148
	v_max_f32_e32 v88, 0, v88
	v_max_f32_e32 v89, 0, v89
	v_ashrrev_i32_e32 v97, 31, v96
	v_mul_f32_e32 v94, v88, v88
	v_mul_f32_e32 v90, v89, v89
	v_max_f32_e32 v88, v95, v95
	v_max_f32_e32 v89, v91, v91
	v_max_f32_e32 v84, v84, v84
	v_max_f32_e32 v80, v80, v80
	v_max_f32_e32 v85, v85, v85
	v_max_f32_e32 v81, v81, v81
	v_max_f32_e32 v86, v86, v86
	v_max_f32_e32 v82, v82, v82
	v_max_f32_e32 v87, v87, v87
	v_max_f32_e32 v83, v83, v83
	v_lshlrev_b64 v[96:97], 14, v[96:97]
	v_max_f32_e32 v92, v92, v92
	v_max_f32_e32 v88, 0, v88
	v_max_f32_e32 v89, 0, v89
	v_max_f32_e32 v84, 0, v84
	v_max_f32_e32 v80, 0, v80
	v_max_f32_e32 v85, 0, v85
	v_max_f32_e32 v81, 0, v81
	v_max_f32_e32 v86, 0, v86
	v_max_f32_e32 v82, 0, v82
	v_max_f32_e32 v87, 0, v87
	v_max_f32_e32 v83, 0, v83
	v_max_f32_e32 v92, 0, v92
	v_mul_f32_e32 v95, v88, v88
	v_mul_f32_e32 v91, v89, v89
	v_lshl_add_u64 v[88:89], s[28:29], 0, v[96:97]
	v_mul_f32_e32 v84, v84, v84
	v_mul_f32_e32 v80, v80, v80
	v_mul_f32_e32 v85, v85, v85
	v_mul_f32_e32 v81, v81, v81
	v_mul_f32_e32 v86, v86, v86
	v_mul_f32_e32 v82, v82, v82
	v_mul_f32_e32 v87, v87, v87
	v_mul_f32_e32 v83, v83, v83
	v_max_f32_e32 v72, v72, v72
	v_mul_f32_e32 v98, v92, v92
	v_lshl_add_u64 v[92:93], v[88:89], 0, v[120:121]
	v_cvt_pk_bf16_f32 v83, v82, v83
	v_cvt_pk_bf16_f32 v82, v80, v81
	v_cvt_pk_bf16_f32 v81, v86, v87
	v_cvt_pk_bf16_f32 v80, v84, v85
	v_max_f32_e32 v72, 0, v72
	global_store_dwordx4 v[92:93], v[80:83], off offset:256
	v_max_f32_e32 v73, v73, v73
	v_max_f32_e32 v73, 0, v73
	v_mul_f32_e32 v83, v72, v72
	v_max_f32_e32 v72, v77, v77
	v_max_f32_e32 v72, 0, v72
	v_mul_f32_e32 v84, v72, v72
	v_mul_f32_e32 v85, v73, v73
	v_max_f32_e32 v72, v78, v78
	v_max_f32_e32 v73, v74, v74
	v_or_b32_e32 v80, 48, v148
	v_max_f32_e32 v72, 0, v72
	v_max_f32_e32 v73, 0, v73
	v_ashrrev_i32_e32 v81, 31, v80
	v_mul_f32_e32 v78, v72, v72
	v_mul_f32_e32 v74, v73, v73
	v_max_f32_e32 v72, v79, v79
	v_max_f32_e32 v73, v75, v75
	v_max_f32_e32 v68, v68, v68
	v_max_f32_e32 v64, v64, v64
	v_max_f32_e32 v69, v69, v69
	v_max_f32_e32 v65, v65, v65
	v_max_f32_e32 v70, v70, v70
	v_max_f32_e32 v66, v66, v66
	v_max_f32_e32 v71, v71, v71
	v_max_f32_e32 v67, v67, v67
	v_lshlrev_b64 v[80:81], 14, v[80:81]
	v_max_f32_e32 v76, v76, v76
	v_max_f32_e32 v72, 0, v72
	v_max_f32_e32 v73, 0, v73
	v_max_f32_e32 v68, 0, v68
	v_max_f32_e32 v64, 0, v64
	v_max_f32_e32 v69, 0, v69
	v_max_f32_e32 v65, 0, v65
	v_max_f32_e32 v70, 0, v70
	v_max_f32_e32 v66, 0, v66
	v_max_f32_e32 v71, 0, v71
	v_max_f32_e32 v67, 0, v67
	v_max_f32_e32 v76, 0, v76
	v_mul_f32_e32 v79, v72, v72
	v_mul_f32_e32 v75, v73, v73
	v_lshl_add_u64 v[72:73], s[28:29], 0, v[80:81]
	v_mul_f32_e32 v68, v68, v68
	v_mul_f32_e32 v64, v64, v64
	v_mul_f32_e32 v69, v69, v69
	v_mul_f32_e32 v65, v65, v65
	v_mul_f32_e32 v70, v70, v70
	v_mul_f32_e32 v66, v66, v66
	v_mul_f32_e32 v71, v71, v71
	v_mul_f32_e32 v67, v67, v67
	v_max_f32_e32 v56, v56, v56
	v_mul_f32_e32 v82, v76, v76
	v_lshl_add_u64 v[76:77], v[72:73], 0, v[120:121]
	v_cvt_pk_bf16_f32 v67, v66, v67
	v_cvt_pk_bf16_f32 v66, v64, v65
	v_cvt_pk_bf16_f32 v65, v70, v71
	v_cvt_pk_bf16_f32 v64, v68, v69
	v_max_f32_e32 v56, 0, v56
	global_store_dwordx4 v[76:77], v[64:67], off offset:256
	v_max_f32_e32 v57, v57, v57
	v_max_f32_e32 v57, 0, v57
	v_mul_f32_e32 v67, v56, v56
	v_max_f32_e32 v56, v61, v61
	v_max_f32_e32 v56, 0, v56
	v_mul_f32_e32 v68, v56, v56
	v_mul_f32_e32 v69, v57, v57
	v_max_f32_e32 v56, v62, v62
	v_max_f32_e32 v57, v58, v58
	v_add_u32_e32 v64, 0x80, v148
	v_max_f32_e32 v56, 0, v56
	v_max_f32_e32 v57, 0, v57
	v_ashrrev_i32_e32 v65, 31, v64
	v_mul_f32_e32 v62, v56, v56
	v_mul_f32_e32 v58, v57, v57
	v_max_f32_e32 v56, v63, v63
	v_max_f32_e32 v57, v59, v59
	v_max_f32_e32 v52, v52, v52
	v_max_f32_e32 v48, v48, v48
	v_max_f32_e32 v53, v53, v53
	v_max_f32_e32 v49, v49, v49
	v_max_f32_e32 v54, v54, v54
	v_max_f32_e32 v50, v50, v50
	v_max_f32_e32 v55, v55, v55
	v_max_f32_e32 v51, v51, v51
	v_lshlrev_b64 v[64:65], 14, v[64:65]
	v_max_f32_e32 v60, v60, v60
	v_max_f32_e32 v56, 0, v56
	v_max_f32_e32 v57, 0, v57
	v_max_f32_e32 v52, 0, v52
	v_max_f32_e32 v48, 0, v48
	v_max_f32_e32 v53, 0, v53
	v_max_f32_e32 v49, 0, v49
	v_max_f32_e32 v54, 0, v54
	v_max_f32_e32 v50, 0, v50
	v_max_f32_e32 v55, 0, v55
	v_max_f32_e32 v51, 0, v51
	v_max_f32_e32 v60, 0, v60
	v_mul_f32_e32 v63, v56, v56
	v_mul_f32_e32 v59, v57, v57
	v_lshl_add_u64 v[56:57], s[28:29], 0, v[64:65]
	v_mul_f32_e32 v52, v52, v52
	v_mul_f32_e32 v48, v48, v48
	v_mul_f32_e32 v53, v53, v53
	v_mul_f32_e32 v49, v49, v49
	v_mul_f32_e32 v54, v54, v54
	v_mul_f32_e32 v50, v50, v50
	v_mul_f32_e32 v55, v55, v55
	v_mul_f32_e32 v51, v51, v51
	v_max_f32_e32 v40, v40, v40
	v_mul_f32_e32 v66, v60, v60
	v_lshl_add_u64 v[60:61], v[56:57], 0, v[120:121]
	v_cvt_pk_bf16_f32 v51, v50, v51
	v_cvt_pk_bf16_f32 v50, v48, v49
	v_cvt_pk_bf16_f32 v49, v54, v55
	v_cvt_pk_bf16_f32 v48, v52, v53
	v_max_f32_e32 v40, 0, v40
	global_store_dwordx4 v[60:61], v[48:51], off offset:256
	v_max_f32_e32 v41, v41, v41
	v_max_f32_e32 v41, 0, v41
	v_mul_f32_e32 v51, v40, v40
	v_max_f32_e32 v40, v45, v45
	v_max_f32_e32 v40, 0, v40
	v_mul_f32_e32 v52, v40, v40
	v_mul_f32_e32 v53, v41, v41
	v_max_f32_e32 v40, v46, v46
	v_max_f32_e32 v41, v42, v42
	v_add_u32_e32 v48, 0x90, v148
	v_max_f32_e32 v40, 0, v40
	v_max_f32_e32 v41, 0, v41
	v_ashrrev_i32_e32 v49, 31, v48
	v_mul_f32_e32 v46, v40, v40
	v_mul_f32_e32 v42, v41, v41
	v_max_f32_e32 v40, v47, v47
	v_max_f32_e32 v41, v43, v43
	v_max_f32_e32 v36, v36, v36
	v_max_f32_e32 v32, v32, v32
	v_max_f32_e32 v37, v37, v37
	v_max_f32_e32 v33, v33, v33
	v_max_f32_e32 v38, v38, v38
	v_max_f32_e32 v34, v34, v34
	v_max_f32_e32 v39, v39, v39
	v_max_f32_e32 v35, v35, v35
	v_lshlrev_b64 v[48:49], 14, v[48:49]
	v_max_f32_e32 v44, v44, v44
	v_max_f32_e32 v40, 0, v40
	v_max_f32_e32 v41, 0, v41
	v_max_f32_e32 v36, 0, v36
	v_max_f32_e32 v32, 0, v32
	v_max_f32_e32 v37, 0, v37
	v_max_f32_e32 v33, 0, v33
	v_max_f32_e32 v38, 0, v38
	v_max_f32_e32 v34, 0, v34
	v_max_f32_e32 v39, 0, v39
	v_max_f32_e32 v35, 0, v35
	v_max_f32_e32 v44, 0, v44
	v_mul_f32_e32 v47, v40, v40
	v_mul_f32_e32 v43, v41, v41
	v_lshl_add_u64 v[40:41], s[28:29], 0, v[48:49]
	v_mul_f32_e32 v36, v36, v36
	v_mul_f32_e32 v32, v32, v32
	v_mul_f32_e32 v37, v37, v37
	v_mul_f32_e32 v33, v33, v33
	v_mul_f32_e32 v38, v38, v38
	v_mul_f32_e32 v34, v34, v34
	v_mul_f32_e32 v39, v39, v39
	v_mul_f32_e32 v35, v35, v35
	v_max_f32_e32 v24, v24, v24
	v_mul_f32_e32 v50, v44, v44
	v_lshl_add_u64 v[44:45], v[40:41], 0, v[120:121]
	v_cvt_pk_bf16_f32 v35, v34, v35
	v_cvt_pk_bf16_f32 v34, v32, v33
	v_cvt_pk_bf16_f32 v33, v38, v39
	v_cvt_pk_bf16_f32 v32, v36, v37
	v_max_f32_e32 v24, 0, v24
	global_store_dwordx4 v[44:45], v[32:35], off offset:256
	v_max_f32_e32 v25, v25, v25
	v_max_f32_e32 v25, 0, v25
	v_mul_f32_e32 v35, v24, v24
	v_max_f32_e32 v24, v29, v29
	v_max_f32_e32 v24, 0, v24
	v_mul_f32_e32 v36, v24, v24
	v_mul_f32_e32 v37, v25, v25
	v_max_f32_e32 v24, v30, v30
	v_max_f32_e32 v25, v26, v26
	v_add_u32_e32 v32, 0xa0, v148
	v_max_f32_e32 v24, 0, v24
	v_max_f32_e32 v25, 0, v25
	v_ashrrev_i32_e32 v33, 31, v32
	v_mul_f32_e32 v30, v24, v24
	v_mul_f32_e32 v26, v25, v25
	v_max_f32_e32 v24, v31, v31
	v_max_f32_e32 v25, v27, v27
	v_max_f32_e32 v20, v20, v20
	v_max_f32_e32 v16, v16, v16
	v_max_f32_e32 v21, v21, v21
	v_max_f32_e32 v17, v17, v17
	v_max_f32_e32 v22, v22, v22
	v_max_f32_e32 v18, v18, v18
	v_max_f32_e32 v23, v23, v23
	v_max_f32_e32 v19, v19, v19
	v_lshlrev_b64 v[32:33], 14, v[32:33]
	v_max_f32_e32 v28, v28, v28
	v_max_f32_e32 v24, 0, v24
	v_max_f32_e32 v25, 0, v25
	v_max_f32_e32 v20, 0, v20
	v_max_f32_e32 v16, 0, v16
	v_max_f32_e32 v21, 0, v21
	v_max_f32_e32 v17, 0, v17
	v_max_f32_e32 v22, 0, v22
	v_max_f32_e32 v18, 0, v18
	v_max_f32_e32 v23, 0, v23
	v_max_f32_e32 v19, 0, v19
	v_max_f32_e32 v28, 0, v28
	v_mul_f32_e32 v31, v24, v24
	v_mul_f32_e32 v27, v25, v25
	v_lshl_add_u64 v[24:25], s[28:29], 0, v[32:33]
	v_mul_f32_e32 v20, v20, v20
	v_mul_f32_e32 v16, v16, v16
	v_mul_f32_e32 v21, v21, v21
	v_mul_f32_e32 v17, v17, v17
	v_mul_f32_e32 v22, v22, v22
	v_mul_f32_e32 v18, v18, v18
	v_mul_f32_e32 v23, v23, v23
	v_mul_f32_e32 v19, v19, v19
	v_max_f32_e32 v8, v8, v8
	v_mul_f32_e32 v34, v28, v28
	v_lshl_add_u64 v[28:29], v[24:25], 0, v[120:121]
	v_cvt_pk_bf16_f32 v19, v18, v19
	v_cvt_pk_bf16_f32 v18, v16, v17
	v_cvt_pk_bf16_f32 v17, v22, v23
	v_cvt_pk_bf16_f32 v16, v20, v21
	v_max_f32_e32 v8, 0, v8
	global_store_dwordx4 v[28:29], v[16:19], off offset:256
	v_max_f32_e32 v9, v9, v9
	v_max_f32_e32 v9, 0, v9
	v_mul_f32_e32 v19, v8, v8
	v_max_f32_e32 v8, v13, v13
	v_max_f32_e32 v8, 0, v8
	v_mul_f32_e32 v20, v8, v8
	v_mul_f32_e32 v21, v9, v9
	v_max_f32_e32 v8, v14, v14
	v_max_f32_e32 v9, v10, v10
	v_add_u32_e32 v16, 0xb0, v148
	v_max_f32_e32 v8, 0, v8
	v_max_f32_e32 v9, 0, v9
	v_ashrrev_i32_e32 v17, 31, v16
	v_max_f32_e32 v12, v12, v12
	v_mul_f32_e32 v14, v8, v8
	v_mul_f32_e32 v10, v9, v9
	v_max_f32_e32 v8, v15, v15
	v_max_f32_e32 v9, v11, v11
	v_max_f32_e32 v4, v4, v4
	v_max_f32_e32 v0, v0, v0
	v_max_f32_e32 v5, v5, v5
	v_max_f32_e32 v1, v1, v1
	v_max_f32_e32 v6, v6, v6
	v_max_f32_e32 v2, v2, v2
	v_max_f32_e32 v7, v7, v7
	v_max_f32_e32 v3, v3, v3
	v_lshlrev_b64 v[16:17], 14, v[16:17]
	v_max_f32_e32 v12, 0, v12
	v_max_f32_e32 v8, 0, v8
	v_max_f32_e32 v9, 0, v9
	v_max_f32_e32 v4, 0, v4
	v_max_f32_e32 v0, 0, v0
	v_max_f32_e32 v5, 0, v5
	v_max_f32_e32 v1, 0, v1
	v_max_f32_e32 v6, 0, v6
	v_max_f32_e32 v2, 0, v2
	v_max_f32_e32 v7, 0, v7
	v_max_f32_e32 v3, 0, v3
	v_mul_f32_e32 v18, v12, v12
	v_mul_f32_e32 v15, v8, v8
	v_mul_f32_e32 v11, v9, v9
	v_lshl_add_u64 v[8:9], s[28:29], 0, v[16:17]
	v_mul_f32_e32 v4, v4, v4
	v_mul_f32_e32 v0, v0, v0
	v_mul_f32_e32 v5, v5, v5
	v_mul_f32_e32 v1, v1, v1
	v_mul_f32_e32 v6, v6, v6
	v_mul_f32_e32 v2, v2, v2
	v_mul_f32_e32 v7, v7, v7
	v_mul_f32_e32 v3, v3, v3
	v_cvt_pk_bf16_f32 v125, v125, v162
	v_cvt_pk_bf16_f32 v124, v124, v159
	v_cvt_pk_bf16_f32 v123, v160, v161
	v_cvt_pk_bf16_f32 v122, v149, v158
	v_cvt_pk_bf16_f32 v107, v106, v107
	v_cvt_pk_bf16_f32 v106, v115, v117
	v_cvt_pk_bf16_f32 v105, v110, v111
	v_cvt_pk_bf16_f32 v104, v114, v116
	v_cvt_pk_bf16_f32 v91, v90, v91
	v_cvt_pk_bf16_f32 v90, v99, v101
	v_cvt_pk_bf16_f32 v89, v94, v95
	v_cvt_pk_bf16_f32 v88, v98, v100
	v_cvt_pk_bf16_f32 v75, v74, v75
	v_cvt_pk_bf16_f32 v74, v83, v85
	v_cvt_pk_bf16_f32 v73, v78, v79
	v_cvt_pk_bf16_f32 v72, v82, v84
	v_cvt_pk_bf16_f32 v59, v58, v59
	v_cvt_pk_bf16_f32 v58, v67, v69
	v_cvt_pk_bf16_f32 v57, v62, v63
	v_cvt_pk_bf16_f32 v56, v66, v68
	v_cvt_pk_bf16_f32 v43, v42, v43
	v_cvt_pk_bf16_f32 v42, v51, v53
	v_cvt_pk_bf16_f32 v41, v46, v47
	v_cvt_pk_bf16_f32 v40, v50, v52
	v_cvt_pk_bf16_f32 v27, v26, v27
	v_cvt_pk_bf16_f32 v26, v35, v37
	v_cvt_pk_bf16_f32 v25, v30, v31
	v_cvt_pk_bf16_f32 v24, v34, v36
	v_lshl_add_u64 v[12:13], v[8:9], 0, v[120:121]
	v_cvt_pk_bf16_f32 v11, v10, v11
	v_cvt_pk_bf16_f32 v10, v19, v21
	v_cvt_pk_bf16_f32 v9, v14, v15
	v_cvt_pk_bf16_f32 v8, v18, v20
	v_cvt_pk_bf16_f32 v3, v2, v3
	v_cvt_pk_bf16_f32 v2, v0, v1
	v_cvt_pk_bf16_f32 v1, v6, v7
	v_cvt_pk_bf16_f32 v0, v4, v5
	global_store_dwordx4 v[126:127], v[122:125], off
	global_store_dwordx4 v[108:109], v[104:107], off
	global_store_dwordx4 v[92:93], v[88:91], off
	global_store_dwordx4 v[76:77], v[72:75], off
	global_store_dwordx4 v[60:61], v[56:59], off
	global_store_dwordx4 v[44:45], v[40:43], off
	global_store_dwordx4 v[28:29], v[24:27], off
	global_store_dwordx4 v[12:13], v[8:11], off
	global_store_dwordx4 v[12:13], v[0:3], off offset:256
.Ldup_nl_mlpin1:
	s_cmp_gt_u32 s52, 29
	s_barrier
	s_cbranch_scc0 .LBB0_1402
	s_cmpk_gt_u32 s12, 0xff
	s_cbranch_scc1 .Ldup_done_mlpin1
	v_lshl_add_u32 v148, s24, 8, v145
	v_max_f32_e32 v124, v124, v124
	v_max_f32_e32 v120, v120, v120
	v_ashrrev_i32_e32 v149, 31, v148
	v_max_f32_e32 v124, 0, v124
	v_max_f32_e32 v120, 0, v120
	v_lshlrev_b64 v[156:157], 14, v[148:149]
	v_mul_f32_e32 v149, v124, v124
	v_mul_f32_e32 v124, v120, v120
	v_max_f32_e32 v120, v125, v125
	v_max_f32_e32 v121, v121, v121
	v_max_f32_e32 v120, 0, v120
	v_max_f32_e32 v121, 0, v121
	v_mul_f32_e32 v158, v120, v120
	v_mul_f32_e32 v159, v121, v121
	v_max_f32_e32 v120, v126, v126
	v_max_f32_e32 v121, v122, v122
	v_max_f32_e32 v120, 0, v120
	v_max_f32_e32 v121, 0, v121
	v_lshl_or_b32 v154, s33, 8, v150
	v_mul_f32_e32 v160, v120, v120
	v_mul_f32_e32 v125, v121, v121
	v_max_f32_e32 v120, v127, v127
	v_max_f32_e32 v121, v123, v123
	v_max_f32_e32 v116, v116, v116
	v_max_f32_e32 v112, v112, v112
	v_max_f32_e32 v117, v117, v117
	v_max_f32_e32 v113, v113, v113
	v_max_f32_e32 v118, v118, v118
	v_max_f32_e32 v114, v114, v114
	v_max_f32_e32 v119, v119, v119
	v_max_f32_e32 v115, v115, v115
	v_ashrrev_i32_e32 v155, 31, v154
	v_max_f32_e32 v120, 0, v120
	v_max_f32_e32 v121, 0, v121
	v_max_f32_e32 v116, 0, v116
	v_max_f32_e32 v112, 0, v112
	v_max_f32_e32 v117, 0, v117
	v_max_f32_e32 v113, 0, v113
	v_max_f32_e32 v118, 0, v118
	v_max_f32_e32 v114, 0, v114
	v_max_f32_e32 v119, 0, v119
	v_max_f32_e32 v115, 0, v115
	v_mul_f32_e32 v161, v120, v120
	v_mul_f32_e32 v162, v121, v121
	v_lshl_add_u64 v[122:123], s[28:29], 0, v[156:157]
	v_lshlrev_b64 v[120:121], 1, v[154:155]
	v_mul_f32_e32 v116, v116, v116
	v_mul_f32_e32 v112, v112, v112
	v_mul_f32_e32 v117, v117, v117
	v_mul_f32_e32 v113, v113, v113
	v_mul_f32_e32 v118, v118, v118
	v_mul_f32_e32 v114, v114, v114
	v_mul_f32_e32 v119, v119, v119
	v_mul_f32_e32 v115, v115, v115
	v_max_f32_e32 v104, v104, v104
	v_lshl_add_u64 v[126:127], v[122:123], 0, v[120:121]
	v_cvt_pk_bf16_f32 v115, v114, v115
	v_cvt_pk_bf16_f32 v114, v112, v113
	v_cvt_pk_bf16_f32 v113, v118, v119
	v_cvt_pk_bf16_f32 v112, v116, v117
	v_max_f32_e32 v104, 0, v104
	global_store_dwordx4 v[126:127], v[112:115], off offset:256
	v_max_f32_e32 v105, v105, v105
	v_max_f32_e32 v105, 0, v105
	v_mul_f32_e32 v115, v104, v104
	v_max_f32_e32 v104, v109, v109
	v_max_f32_e32 v104, 0, v104
	v_mul_f32_e32 v116, v104, v104
	v_mul_f32_e32 v117, v105, v105
	v_max_f32_e32 v104, v110, v110
	v_max_f32_e32 v105, v106, v106
	v_or_b32_e32 v112, 16, v148
	v_max_f32_e32 v104, 0, v104
	v_max_f32_e32 v105, 0, v105
	v_ashrrev_i32_e32 v113, 31, v112
	v_mul_f32_e32 v110, v104, v104
	v_mul_f32_e32 v106, v105, v105
	v_max_f32_e32 v104, v111, v111
	v_max_f32_e32 v105, v107, v107
	v_max_f32_e32 v100, v100, v100
	v_max_f32_e32 v96, v96, v96
	v_max_f32_e32 v101, v101, v101
	v_max_f32_e32 v97, v97, v97
	v_max_f32_e32 v102, v102, v102
	v_max_f32_e32 v98, v98, v98
	v_max_f32_e32 v103, v103, v103
	v_max_f32_e32 v99, v99, v99
	v_lshlrev_b64 v[112:113], 14, v[112:113]
	v_max_f32_e32 v108, v108, v108
	v_max_f32_e32 v104, 0, v104
	v_max_f32_e32 v105, 0, v105
	v_max_f32_e32 v100, 0, v100
	v_max_f32_e32 v96, 0, v96
	v_max_f32_e32 v101, 0, v101
	v_max_f32_e32 v97, 0, v97
	v_max_f32_e32 v102, 0, v102
	v_max_f32_e32 v98, 0, v98
	v_max_f32_e32 v103, 0, v103
	v_max_f32_e32 v99, 0, v99
	v_max_f32_e32 v108, 0, v108
	v_mul_f32_e32 v111, v104, v104
	v_mul_f32_e32 v107, v105, v105
	v_lshl_add_u64 v[104:105], s[28:29], 0, v[112:113]
	v_mul_f32_e32 v100, v100, v100
	v_mul_f32_e32 v96, v96, v96
	v_mul_f32_e32 v101, v101, v101
	v_mul_f32_e32 v97, v97, v97
	v_mul_f32_e32 v102, v102, v102
	v_mul_f32_e32 v98, v98, v98
	v_mul_f32_e32 v103, v103, v103
	v_mul_f32_e32 v99, v99, v99
	v_max_f32_e32 v88, v88, v88
	v_mul_f32_e32 v114, v108, v108
	v_lshl_add_u64 v[108:109], v[104:105], 0, v[120:121]
	v_cvt_pk_bf16_f32 v99, v98, v99
	v_cvt_pk_bf16_f32 v98, v96, v97
	v_cvt_pk_bf16_f32 v97, v102, v103
	v_cvt_pk_bf16_f32 v96, v100, v101
	v_max_f32_e32 v88, 0, v88
	global_store_dwordx4 v[108:109], v[96:99], off offset:256
	v_max_f32_e32 v89, v89, v89
	v_max_f32_e32 v89, 0, v89
	v_mul_f32_e32 v99, v88, v88
	v_max_f32_e32 v88, v93, v93
	v_max_f32_e32 v88, 0, v88
	v_mul_f32_e32 v100, v88, v88
	v_mul_f32_e32 v101, v89, v89
	v_max_f32_e32 v88, v94, v94
	v_max_f32_e32 v89, v90, v90
	v_or_b32_e32 v96, 32, v148
	v_max_f32_e32 v88, 0, v88
	v_max_f32_e32 v89, 0, v89
	v_ashrrev_i32_e32 v97, 31, v96
	v_mul_f32_e32 v94, v88, v88
	v_mul_f32_e32 v90, v89, v89
	v_max_f32_e32 v88, v95, v95
	v_max_f32_e32 v89, v91, v91
	v_max_f32_e32 v84, v84, v84
	v_max_f32_e32 v80, v80, v80
	v_max_f32_e32 v85, v85, v85
	v_max_f32_e32 v81, v81, v81
	v_max_f32_e32 v86, v86, v86
	v_max_f32_e32 v82, v82, v82
	v_max_f32_e32 v87, v87, v87
	v_max_f32_e32 v83, v83, v83
	v_lshlrev_b64 v[96:97], 14, v[96:97]
	v_max_f32_e32 v92, v92, v92
	v_max_f32_e32 v88, 0, v88
	v_max_f32_e32 v89, 0, v89
	v_max_f32_e32 v84, 0, v84
	v_max_f32_e32 v80, 0, v80
	v_max_f32_e32 v85, 0, v85
	v_max_f32_e32 v81, 0, v81
	v_max_f32_e32 v86, 0, v86
	v_max_f32_e32 v82, 0, v82
	v_max_f32_e32 v87, 0, v87
	v_max_f32_e32 v83, 0, v83
	v_max_f32_e32 v92, 0, v92
	v_mul_f32_e32 v95, v88, v88
	v_mul_f32_e32 v91, v89, v89
	v_lshl_add_u64 v[88:89], s[28:29], 0, v[96:97]
	v_mul_f32_e32 v84, v84, v84
	v_mul_f32_e32 v80, v80, v80
	v_mul_f32_e32 v85, v85, v85
	v_mul_f32_e32 v81, v81, v81
	v_mul_f32_e32 v86, v86, v86
	v_mul_f32_e32 v82, v82, v82
	v_mul_f32_e32 v87, v87, v87
	v_mul_f32_e32 v83, v83, v83
	v_max_f32_e32 v72, v72, v72
	v_mul_f32_e32 v98, v92, v92
	v_lshl_add_u64 v[92:93], v[88:89], 0, v[120:121]
	v_cvt_pk_bf16_f32 v83, v82, v83
	v_cvt_pk_bf16_f32 v82, v80, v81
	v_cvt_pk_bf16_f32 v81, v86, v87
	v_cvt_pk_bf16_f32 v80, v84, v85
	v_max_f32_e32 v72, 0, v72
	global_store_dwordx4 v[92:93], v[80:83], off offset:256
	v_max_f32_e32 v73, v73, v73
	v_max_f32_e32 v73, 0, v73
	v_mul_f32_e32 v83, v72, v72
	v_max_f32_e32 v72, v77, v77
	v_max_f32_e32 v72, 0, v72
	v_mul_f32_e32 v84, v72, v72
	v_mul_f32_e32 v85, v73, v73
	v_max_f32_e32 v72, v78, v78
	v_max_f32_e32 v73, v74, v74
	v_or_b32_e32 v80, 48, v148
	v_max_f32_e32 v72, 0, v72
	v_max_f32_e32 v73, 0, v73
	v_ashrrev_i32_e32 v81, 31, v80
	v_mul_f32_e32 v78, v72, v72
	v_mul_f32_e32 v74, v73, v73
	v_max_f32_e32 v72, v79, v79
	v_max_f32_e32 v73, v75, v75
	v_max_f32_e32 v68, v68, v68
	v_max_f32_e32 v64, v64, v64
	v_max_f32_e32 v69, v69, v69
	v_max_f32_e32 v65, v65, v65
	v_max_f32_e32 v70, v70, v70
	v_max_f32_e32 v66, v66, v66
	v_max_f32_e32 v71, v71, v71
	v_max_f32_e32 v67, v67, v67
	v_lshlrev_b64 v[80:81], 14, v[80:81]
	v_max_f32_e32 v76, v76, v76
	v_max_f32_e32 v72, 0, v72
	v_max_f32_e32 v73, 0, v73
	v_max_f32_e32 v68, 0, v68
	v_max_f32_e32 v64, 0, v64
	v_max_f32_e32 v69, 0, v69
	v_max_f32_e32 v65, 0, v65
	v_max_f32_e32 v70, 0, v70
	v_max_f32_e32 v66, 0, v66
	v_max_f32_e32 v71, 0, v71
	v_max_f32_e32 v67, 0, v67
	v_max_f32_e32 v76, 0, v76
	v_mul_f32_e32 v79, v72, v72
	v_mul_f32_e32 v75, v73, v73
	v_lshl_add_u64 v[72:73], s[28:29], 0, v[80:81]
	v_mul_f32_e32 v68, v68, v68
	v_mul_f32_e32 v64, v64, v64
	v_mul_f32_e32 v69, v69, v69
	v_mul_f32_e32 v65, v65, v65
	v_mul_f32_e32 v70, v70, v70
	v_mul_f32_e32 v66, v66, v66
	v_mul_f32_e32 v71, v71, v71
	v_mul_f32_e32 v67, v67, v67
	v_max_f32_e32 v56, v56, v56
	v_mul_f32_e32 v82, v76, v76
	v_lshl_add_u64 v[76:77], v[72:73], 0, v[120:121]
	v_cvt_pk_bf16_f32 v67, v66, v67
	v_cvt_pk_bf16_f32 v66, v64, v65
	v_cvt_pk_bf16_f32 v65, v70, v71
	v_cvt_pk_bf16_f32 v64, v68, v69
	v_max_f32_e32 v56, 0, v56
	global_store_dwordx4 v[76:77], v[64:67], off offset:256
	v_max_f32_e32 v57, v57, v57
	v_max_f32_e32 v57, 0, v57
	v_mul_f32_e32 v67, v56, v56
	v_max_f32_e32 v56, v61, v61
	v_max_f32_e32 v56, 0, v56
	v_mul_f32_e32 v68, v56, v56
	v_mul_f32_e32 v69, v57, v57
	v_max_f32_e32 v56, v62, v62
	v_max_f32_e32 v57, v58, v58
	v_add_u32_e32 v64, 0x80, v148
	v_max_f32_e32 v56, 0, v56
	v_max_f32_e32 v57, 0, v57
	v_ashrrev_i32_e32 v65, 31, v64
	v_mul_f32_e32 v62, v56, v56
	v_mul_f32_e32 v58, v57, v57
	v_max_f32_e32 v56, v63, v63
	v_max_f32_e32 v57, v59, v59
	v_max_f32_e32 v52, v52, v52
	v_max_f32_e32 v48, v48, v48
	v_max_f32_e32 v53, v53, v53
	v_max_f32_e32 v49, v49, v49
	v_max_f32_e32 v54, v54, v54
	v_max_f32_e32 v50, v50, v50
	v_max_f32_e32 v55, v55, v55
	v_max_f32_e32 v51, v51, v51
	v_lshlrev_b64 v[64:65], 14, v[64:65]
	v_max_f32_e32 v60, v60, v60
	v_max_f32_e32 v56, 0, v56
	v_max_f32_e32 v57, 0, v57
	v_max_f32_e32 v52, 0, v52
	v_max_f32_e32 v48, 0, v48
	v_max_f32_e32 v53, 0, v53
	v_max_f32_e32 v49, 0, v49
	v_max_f32_e32 v54, 0, v54
	v_max_f32_e32 v50, 0, v50
	v_max_f32_e32 v55, 0, v55
	v_max_f32_e32 v51, 0, v51
	v_max_f32_e32 v60, 0, v60
	v_mul_f32_e32 v63, v56, v56
	v_mul_f32_e32 v59, v57, v57
	v_lshl_add_u64 v[56:57], s[28:29], 0, v[64:65]
	v_mul_f32_e32 v52, v52, v52
	v_mul_f32_e32 v48, v48, v48
	v_mul_f32_e32 v53, v53, v53
	v_mul_f32_e32 v49, v49, v49
	v_mul_f32_e32 v54, v54, v54
	v_mul_f32_e32 v50, v50, v50
	v_mul_f32_e32 v55, v55, v55
	v_mul_f32_e32 v51, v51, v51
	v_max_f32_e32 v40, v40, v40
	v_mul_f32_e32 v66, v60, v60
	v_lshl_add_u64 v[60:61], v[56:57], 0, v[120:121]
	v_cvt_pk_bf16_f32 v51, v50, v51
	v_cvt_pk_bf16_f32 v50, v48, v49
	v_cvt_pk_bf16_f32 v49, v54, v55
	v_cvt_pk_bf16_f32 v48, v52, v53
	v_max_f32_e32 v40, 0, v40
	global_store_dwordx4 v[60:61], v[48:51], off offset:256
	v_max_f32_e32 v41, v41, v41
	v_max_f32_e32 v41, 0, v41
	v_mul_f32_e32 v51, v40, v40
	v_max_f32_e32 v40, v45, v45
	v_max_f32_e32 v40, 0, v40
	v_mul_f32_e32 v52, v40, v40
	v_mul_f32_e32 v53, v41, v41
	v_max_f32_e32 v40, v46, v46
	v_max_f32_e32 v41, v42, v42
	v_add_u32_e32 v48, 0x90, v148
	v_max_f32_e32 v40, 0, v40
	v_max_f32_e32 v41, 0, v41
	v_ashrrev_i32_e32 v49, 31, v48
	v_mul_f32_e32 v46, v40, v40
	v_mul_f32_e32 v42, v41, v41
	v_max_f32_e32 v40, v47, v47
	v_max_f32_e32 v41, v43, v43
	v_max_f32_e32 v36, v36, v36
	v_max_f32_e32 v32, v32, v32
	v_max_f32_e32 v37, v37, v37
	v_max_f32_e32 v33, v33, v33
	v_max_f32_e32 v38, v38, v38
	v_max_f32_e32 v34, v34, v34
	v_max_f32_e32 v39, v39, v39
	v_max_f32_e32 v35, v35, v35
	v_lshlrev_b64 v[48:49], 14, v[48:49]
	v_max_f32_e32 v44, v44, v44
	v_max_f32_e32 v40, 0, v40
	v_max_f32_e32 v41, 0, v41
	v_max_f32_e32 v36, 0, v36
	v_max_f32_e32 v32, 0, v32
	v_max_f32_e32 v37, 0, v37
	v_max_f32_e32 v33, 0, v33
	v_max_f32_e32 v38, 0, v38
	v_max_f32_e32 v34, 0, v34
	v_max_f32_e32 v39, 0, v39
	v_max_f32_e32 v35, 0, v35
	v_max_f32_e32 v44, 0, v44
	v_mul_f32_e32 v47, v40, v40
	v_mul_f32_e32 v43, v41, v41
	v_lshl_add_u64 v[40:41], s[28:29], 0, v[48:49]
	v_mul_f32_e32 v36, v36, v36
	v_mul_f32_e32 v32, v32, v32
	v_mul_f32_e32 v37, v37, v37
	v_mul_f32_e32 v33, v33, v33
	v_mul_f32_e32 v38, v38, v38
	v_mul_f32_e32 v34, v34, v34
	v_mul_f32_e32 v39, v39, v39
	v_mul_f32_e32 v35, v35, v35
	v_max_f32_e32 v24, v24, v24
	v_mul_f32_e32 v50, v44, v44
	v_lshl_add_u64 v[44:45], v[40:41], 0, v[120:121]
	v_cvt_pk_bf16_f32 v35, v34, v35
	v_cvt_pk_bf16_f32 v34, v32, v33
	v_cvt_pk_bf16_f32 v33, v38, v39
	v_cvt_pk_bf16_f32 v32, v36, v37
	v_max_f32_e32 v24, 0, v24
	global_store_dwordx4 v[44:45], v[32:35], off offset:256
	v_max_f32_e32 v25, v25, v25
	v_max_f32_e32 v25, 0, v25
	v_mul_f32_e32 v35, v24, v24
	v_max_f32_e32 v24, v29, v29
	v_max_f32_e32 v24, 0, v24
	v_mul_f32_e32 v36, v24, v24
	v_mul_f32_e32 v37, v25, v25
	v_max_f32_e32 v24, v30, v30
	v_max_f32_e32 v25, v26, v26
	v_add_u32_e32 v32, 0xa0, v148
	v_max_f32_e32 v24, 0, v24
	v_max_f32_e32 v25, 0, v25
	v_ashrrev_i32_e32 v33, 31, v32
	v_mul_f32_e32 v30, v24, v24
	v_mul_f32_e32 v26, v25, v25
	v_max_f32_e32 v24, v31, v31
	v_max_f32_e32 v25, v27, v27
	v_max_f32_e32 v20, v20, v20
	v_max_f32_e32 v16, v16, v16
	v_max_f32_e32 v21, v21, v21
	v_max_f32_e32 v17, v17, v17
	v_max_f32_e32 v22, v22, v22
	v_max_f32_e32 v18, v18, v18
	v_max_f32_e32 v23, v23, v23
	v_max_f32_e32 v19, v19, v19
	v_lshlrev_b64 v[32:33], 14, v[32:33]
	v_max_f32_e32 v28, v28, v28
	v_max_f32_e32 v24, 0, v24
	v_max_f32_e32 v25, 0, v25
	v_max_f32_e32 v20, 0, v20
	v_max_f32_e32 v16, 0, v16
	v_max_f32_e32 v21, 0, v21
	v_max_f32_e32 v17, 0, v17
	v_max_f32_e32 v22, 0, v22
	v_max_f32_e32 v18, 0, v18
	v_max_f32_e32 v23, 0, v23
	v_max_f32_e32 v19, 0, v19
	v_max_f32_e32 v28, 0, v28
	v_mul_f32_e32 v31, v24, v24
	v_mul_f32_e32 v27, v25, v25
	v_lshl_add_u64 v[24:25], s[28:29], 0, v[32:33]
	v_mul_f32_e32 v20, v20, v20
	v_mul_f32_e32 v16, v16, v16
	v_mul_f32_e32 v21, v21, v21
	v_mul_f32_e32 v17, v17, v17
	v_mul_f32_e32 v22, v22, v22
	v_mul_f32_e32 v18, v18, v18
	v_mul_f32_e32 v23, v23, v23
	v_mul_f32_e32 v19, v19, v19
	v_max_f32_e32 v8, v8, v8
	v_mul_f32_e32 v34, v28, v28
	v_lshl_add_u64 v[28:29], v[24:25], 0, v[120:121]
	v_cvt_pk_bf16_f32 v19, v18, v19
	v_cvt_pk_bf16_f32 v18, v16, v17
	v_cvt_pk_bf16_f32 v17, v22, v23
	v_cvt_pk_bf16_f32 v16, v20, v21
	v_max_f32_e32 v8, 0, v8
	global_store_dwordx4 v[28:29], v[16:19], off offset:256
	v_max_f32_e32 v9, v9, v9
	v_max_f32_e32 v9, 0, v9
	v_mul_f32_e32 v19, v8, v8
	v_max_f32_e32 v8, v13, v13
	v_max_f32_e32 v8, 0, v8
	v_mul_f32_e32 v20, v8, v8
	v_mul_f32_e32 v21, v9, v9
	v_max_f32_e32 v8, v14, v14
	v_max_f32_e32 v9, v10, v10
	v_add_u32_e32 v16, 0xb0, v148
	v_max_f32_e32 v8, 0, v8
	v_max_f32_e32 v9, 0, v9
	v_ashrrev_i32_e32 v17, 31, v16
	v_max_f32_e32 v12, v12, v12
	v_mul_f32_e32 v14, v8, v8
	v_mul_f32_e32 v10, v9, v9
	v_max_f32_e32 v8, v15, v15
	v_max_f32_e32 v9, v11, v11
	v_max_f32_e32 v4, v4, v4
	v_max_f32_e32 v0, v0, v0
	v_max_f32_e32 v5, v5, v5
	v_max_f32_e32 v1, v1, v1
	v_max_f32_e32 v6, v6, v6
	v_max_f32_e32 v2, v2, v2
	v_max_f32_e32 v7, v7, v7
	v_max_f32_e32 v3, v3, v3
	v_lshlrev_b64 v[16:17], 14, v[16:17]
	v_max_f32_e32 v12, 0, v12
	v_max_f32_e32 v8, 0, v8
	v_max_f32_e32 v9, 0, v9
	v_max_f32_e32 v4, 0, v4
	v_max_f32_e32 v0, 0, v0
	v_max_f32_e32 v5, 0, v5
	v_max_f32_e32 v1, 0, v1
	v_max_f32_e32 v6, 0, v6
	v_max_f32_e32 v2, 0, v2
	v_max_f32_e32 v7, 0, v7
	v_max_f32_e32 v3, 0, v3
	v_mul_f32_e32 v18, v12, v12
	v_mul_f32_e32 v15, v8, v8
	v_mul_f32_e32 v11, v9, v9
	v_lshl_add_u64 v[8:9], s[28:29], 0, v[16:17]
	v_mul_f32_e32 v4, v4, v4
	v_mul_f32_e32 v0, v0, v0
	v_mul_f32_e32 v5, v5, v5
	v_mul_f32_e32 v1, v1, v1
	v_mul_f32_e32 v6, v6, v6
	v_mul_f32_e32 v2, v2, v2
	v_mul_f32_e32 v7, v7, v7
	v_mul_f32_e32 v3, v3, v3
	v_cvt_pk_bf16_f32 v125, v125, v162
	v_cvt_pk_bf16_f32 v124, v124, v159
	v_cvt_pk_bf16_f32 v123, v160, v161
	v_cvt_pk_bf16_f32 v122, v149, v158
	v_cvt_pk_bf16_f32 v107, v106, v107
	v_cvt_pk_bf16_f32 v106, v115, v117
	v_cvt_pk_bf16_f32 v105, v110, v111
	v_cvt_pk_bf16_f32 v104, v114, v116
	v_cvt_pk_bf16_f32 v91, v90, v91
	v_cvt_pk_bf16_f32 v90, v99, v101
	v_cvt_pk_bf16_f32 v89, v94, v95
	v_cvt_pk_bf16_f32 v88, v98, v100
	v_cvt_pk_bf16_f32 v75, v74, v75
	v_cvt_pk_bf16_f32 v74, v83, v85
	v_cvt_pk_bf16_f32 v73, v78, v79
	v_cvt_pk_bf16_f32 v72, v82, v84
	v_cvt_pk_bf16_f32 v59, v58, v59
	v_cvt_pk_bf16_f32 v58, v67, v69
	v_cvt_pk_bf16_f32 v57, v62, v63
	v_cvt_pk_bf16_f32 v56, v66, v68
	v_cvt_pk_bf16_f32 v43, v42, v43
	v_cvt_pk_bf16_f32 v42, v51, v53
	v_cvt_pk_bf16_f32 v41, v46, v47
	v_cvt_pk_bf16_f32 v40, v50, v52
	v_cvt_pk_bf16_f32 v27, v26, v27
	v_cvt_pk_bf16_f32 v26, v35, v37
	v_cvt_pk_bf16_f32 v25, v30, v31
	v_cvt_pk_bf16_f32 v24, v34, v36
	v_lshl_add_u64 v[12:13], v[8:9], 0, v[120:121]
	v_cvt_pk_bf16_f32 v11, v10, v11
	v_cvt_pk_bf16_f32 v10, v19, v21
	v_cvt_pk_bf16_f32 v9, v14, v15
	v_cvt_pk_bf16_f32 v8, v18, v20
	v_cvt_pk_bf16_f32 v3, v2, v3
	v_cvt_pk_bf16_f32 v2, v0, v1
	v_cvt_pk_bf16_f32 v1, v6, v7
	v_cvt_pk_bf16_f32 v0, v4, v5
	global_store_dwordx4 v[126:127], v[122:125], off
	global_store_dwordx4 v[108:109], v[104:107], off
	global_store_dwordx4 v[92:93], v[88:91], off
	global_store_dwordx4 v[76:77], v[72:75], off
	global_store_dwordx4 v[60:61], v[56:59], off
	global_store_dwordx4 v[44:45], v[40:43], off
	global_store_dwordx4 v[28:29], v[24:27], off
	global_store_dwordx4 v[12:13], v[8:11], off
	global_store_dwordx4 v[12:13], v[0:3], off offset:256
.Ldup_done_mlpin1:
	s_and_b64 vcc, exec, s[0:1]
	s_mov_b32 s33, s10
	s_mov_b32 s24, s14
	s_mov_b64 s[36:37], s[18:19]
	s_mov_b64 s[26:27], s[16:17]
	s_cbranch_vccz .LBB0_1399
	s_waitcnt vmcnt(0)
	s_cmpk_gt_u32 s12, 0xff
	s_cbranch_scc1 .LBB0_1406
	s_barrier
